# GEMM epilogue 16-byte result stores made write-through (sc1) on top of the deferred o-reduction version
# speedup vs baseline: 1.0063x; 1.0021x over previous
; __device__ __forceinline__ unsigned pk2(float lo, float hi) { return pg8::cvt_pk_bf16(lo, hi); }
;     __device__ __forceinline__ void operator()(const f32x4 (&acc)[2][2][4][2], const pg8::Unit& u, int wr, int wc, int fr, int fq) const {
;         bf16_t* base; int pitch, colt;
;         if (u.pn < 6) { base = PR; pitch = PRW; colt = 256 * u.pn; }
;         else if (u.pn < 12) { base = PH; pitch = PHG; colt = 256 * (u.pn - 6); }
;         else { base = PG; pitch = PGL; colt = 256 * (u.pn - 12); }
;         const int row0 = u.pm * 256 + wr * 64 + fr, col0 = colt + wc * 32 + 8 * fq;
; #pragma unroll
;         for (int ai = 0; ai < 2; ++ai)
; #pragma unroll
;             for (int m = 0; m < 4; ++m) {
;                 bf16_t* rowp = base + (size_t)(row0 + ai * 128 + m * 16) * pitch + col0;
; #pragma unroll
;                 for (int bj = 0; bj < 2; ++bj) {
;                     const f32x4 v0 = acc[ai][bj][m][0], v1 = acc[ai][bj][m][1];
;                     u32x4 w; w.x = pk2(v0[0], v0[1]); w.y = pk2(v0[2], v0[3]); w.z = pk2(v1[0], v1[1]); w.w = pk2(v1[2], v1[3]);
;                     *(u32x4*)(rowp + bj * 128) = w;
;                 }
;             }
;     }
.LBB0_1067:
	v_lshl_add_u32 v152, s38, 8, v146
	v_add_u32_e32 v144, s11, v148
	v_ashrrev_i32_e32 v145, 31, v144
	v_ashrrev_i32_e32 v150, 31, v152
	v_lshl_add_u64 v[144:145], v[144:145], 1, s[20:21]
	v_mul_lo_u32 v153, s18, v150
	v_mul_lo_u32 v154, s19, v152
	v_mad_u64_u32 v[150:151], s[20:21], s18, v152, 0
	v_add3_u32 v151, v151, v153, v154
	v_lshl_add_u64 v[150:151], v[150:151], 1, v[144:145]
	v_cvt_pk_bf16_f32 v126, v126, v127
	v_cvt_pk_bf16_f32 v127, v128, v129
	v_cvt_pk_bf16_f32 v128, v122, v123
	v_cvt_pk_bf16_f32 v129, v124, v125
	global_store_dwordx4 v[150:151], v[126:129], off sc1
	v_cvt_pk_bf16_f32 v114, v114, v115
	v_cvt_pk_bf16_f32 v115, v116, v117
	v_cvt_pk_bf16_f32 v116, v106, v107
	v_or_b32_e32 v106, 16, v152
	v_cvt_pk_bf16_f32 v117, v108, v109
	v_mul_lo_u32 v108, s19, v106
	v_mad_u64_u32 v[106:107], s[20:21], s18, v106, 0
	v_add3_u32 v107, v107, v153, v108
	global_store_dwordx4 v[150:151], v[114:117], off offset:256 sc1
	s_and_b64 vcc, exec, s[4:5]
	s_mov_b32 s39, s10
	v_lshl_add_u64 v[114:115], v[106:107], 1, v[144:145]
	v_cvt_pk_bf16_f32 v106, v118, v119
	v_cvt_pk_bf16_f32 v107, v120, v121
	v_cvt_pk_bf16_f32 v108, v110, v111
	v_cvt_pk_bf16_f32 v109, v112, v113
	global_store_dwordx4 v[114:115], v[106:109], off sc1
	v_cvt_pk_bf16_f32 v98, v98, v99
	v_cvt_pk_bf16_f32 v99, v100, v101
	v_cvt_pk_bf16_f32 v100, v90, v91
	v_or_b32_e32 v90, 32, v152
	v_cvt_pk_bf16_f32 v101, v92, v93
	v_mul_lo_u32 v92, s19, v90
	v_mad_u64_u32 v[90:91], s[20:21], s18, v90, 0
	v_add3_u32 v91, v91, v153, v92
	global_store_dwordx4 v[114:115], v[98:101], off offset:256 sc1
	s_mov_b32 s38, s12
	s_nop 0
	v_lshl_add_u64 v[98:99], v[90:91], 1, v[144:145]
	v_cvt_pk_bf16_f32 v90, v102, v103
	v_cvt_pk_bf16_f32 v91, v104, v105
	v_cvt_pk_bf16_f32 v92, v94, v95
	v_cvt_pk_bf16_f32 v93, v96, v97
	global_store_dwordx4 v[98:99], v[90:93], off sc1
	v_cvt_pk_bf16_f32 v82, v82, v83
	v_cvt_pk_bf16_f32 v83, v84, v85
	v_cvt_pk_bf16_f32 v84, v74, v75
	v_or_b32_e32 v74, 48, v152
	v_cvt_pk_bf16_f32 v85, v76, v77
	v_mul_lo_u32 v76, s19, v74
	v_mad_u64_u32 v[74:75], s[20:21], s18, v74, 0
	v_add3_u32 v75, v75, v153, v76
	global_store_dwordx4 v[98:99], v[82:85], off offset:256 sc1
	s_nop 1
	v_lshl_add_u64 v[82:83], v[74:75], 1, v[144:145]
	v_cvt_pk_bf16_f32 v74, v86, v87
	v_cvt_pk_bf16_f32 v75, v88, v89
	v_cvt_pk_bf16_f32 v76, v78, v79
	v_cvt_pk_bf16_f32 v77, v80, v81
	global_store_dwordx4 v[82:83], v[74:77], off sc1
	v_cvt_pk_bf16_f32 v70, v70, v71
	v_cvt_pk_bf16_f32 v71, v72, v73
	v_cvt_pk_bf16_f32 v72, v66, v67
	v_add_u32_e32 v66, 0x80, v152
	v_ashrrev_i32_e32 v67, 31, v66
	v_cvt_pk_bf16_f32 v73, v68, v69
	v_mul_lo_u32 v68, s18, v67
	v_mul_lo_u32 v69, s19, v66
	v_mad_u64_u32 v[66:67], s[20:21], s18, v66, 0
	v_add3_u32 v67, v67, v68, v69
	v_lshl_add_u64 v[66:67], v[66:67], 1, v[144:145]
	global_store_dwordx4 v[82:83], v[70:73], off offset:256 sc1
	v_cvt_pk_bf16_f32 v62, v62, v63
	v_cvt_pk_bf16_f32 v63, v64, v65
	v_cvt_pk_bf16_f32 v64, v58, v59
	v_cvt_pk_bf16_f32 v65, v60, v61
	global_store_dwordx4 v[66:67], v[62:65], off sc1
	v_cvt_pk_bf16_f32 v54, v54, v55
	v_cvt_pk_bf16_f32 v55, v56, v57
	v_cvt_pk_bf16_f32 v56, v46, v47
	v_add_u32_e32 v46, 0x90, v152
	v_ashrrev_i32_e32 v47, 31, v46
	v_cvt_pk_bf16_f32 v57, v48, v49
	v_mul_lo_u32 v48, s18, v47
	v_mul_lo_u32 v49, s19, v46
	v_mad_u64_u32 v[46:47], s[20:21], s18, v46, 0
	v_add3_u32 v47, v47, v48, v49
	global_store_dwordx4 v[66:67], v[54:57], off offset:256 sc1
	s_nop 1
	v_lshl_add_u64 v[54:55], v[46:47], 1, v[144:145]
	v_cvt_pk_bf16_f32 v46, v50, v51
	v_cvt_pk_bf16_f32 v47, v52, v53
	v_cvt_pk_bf16_f32 v48, v42, v43
	v_cvt_pk_bf16_f32 v49, v44, v45
	global_store_dwordx4 v[54:55], v[46:49], off sc1
	v_cvt_pk_bf16_f32 v38, v38, v39
	v_cvt_pk_bf16_f32 v39, v40, v41
	v_cvt_pk_bf16_f32 v40, v30, v31
	v_add_u32_e32 v30, 0xa0, v152
	v_ashrrev_i32_e32 v31, 31, v30
	v_cvt_pk_bf16_f32 v41, v32, v33
	v_mul_lo_u32 v32, s18, v31
	v_mul_lo_u32 v33, s19, v30
	v_mad_u64_u32 v[30:31], s[20:21], s18, v30, 0
	v_add3_u32 v31, v31, v32, v33
	global_store_dwordx4 v[54:55], v[38:41], off offset:256 sc1
	s_mov_b64 s[20:21], s[16:17]
	s_nop 0
	v_lshl_add_u64 v[38:39], v[30:31], 1, v[144:145]
	v_cvt_pk_bf16_f32 v30, v34, v35
	v_cvt_pk_bf16_f32 v31, v36, v37
	v_cvt_pk_bf16_f32 v32, v26, v27
	v_cvt_pk_bf16_f32 v33, v28, v29
	global_store_dwordx4 v[38:39], v[30:33], off sc1
	v_cvt_pk_bf16_f32 v22, v22, v23
	v_cvt_pk_bf16_f32 v23, v24, v25
	v_cvt_pk_bf16_f32 v24, v14, v15
	v_add_u32_e32 v14, 0xb0, v152
	v_ashrrev_i32_e32 v15, 31, v14
	v_cvt_pk_bf16_f32 v25, v16, v17
	v_mul_lo_u32 v16, s18, v15
	v_mul_lo_u32 v17, s19, v14
	v_mad_u64_u32 v[14:15], s[18:19], s18, v14, 0
	v_add3_u32 v15, v15, v16, v17
	global_store_dwordx4 v[38:39], v[22:25], off offset:256 sc1
	s_mov_b64 s[18:19], s[14:15]
	s_nop 0
	v_lshl_add_u64 v[22:23], v[14:15], 1, v[144:145]
	v_cvt_pk_bf16_f32 v14, v18, v19
	v_cvt_pk_bf16_f32 v15, v20, v21
	v_cvt_pk_bf16_f32 v16, v10, v11
	v_cvt_pk_bf16_f32 v17, v12, v13
	global_store_dwordx4 v[22:23], v[14:17], off sc1
	v_cvt_pk_bf16_f32 v6, v6, v7
	v_cvt_pk_bf16_f32 v7, v8, v9
	v_cvt_pk_bf16_f32 v8, v2, v3
	v_cvt_pk_bf16_f32 v9, v4, v5
	global_store_dwordx4 v[22:23], v[6:9], off offset:256 sc1
	s_cbranch_vccnz .LBB0_1080

; #define PG8_STAGE(bufoff, gbase, voff) do { _Pragma("unroll") for (int _i = 0; _i < 2; ++_i) \
;         __builtin_amdgcn_global_load_lds((const unsigned*)((const char*)(gbase) + (voff)[_i]), (PG8_LAS unsigned*)(lds + (bufoff) + ldsw + _i * 8192), 16, 0, 0); } while (0)
; #define PG8_LDA(dst, b, h) do { _Pragma("unroll") for (int m = 0; m < 4; ++m) _Pragma("unroll") for (int k = 0; k < 2; ++k) dst[m][k] = *(const PG8_LAS bf16x8*)(lds + PG8_SA(b, h) + aoff + m * 2048 + k * 1024); } while (0)
; #define PG8_LDB(dst, b, h) do { _Pragma("unroll") for (int n = 0; n < 2; ++n) _Pragma("unroll") for (int k = 0; k < 2; ++k) dst[n][k] = *(const PG8_LAS bf16x8*)(lds + PG8_SB(b, h) + boff + n * 2048 + k * 1024); } while (0)
; #define PG8_MMA(ai, bj, At, Bt) do { __builtin_amdgcn_s_setprio(1); _Pragma("unroll") for (int m = 0; m < 4; ++m) _Pragma("unroll") for (int n = 0; n < 2; ++n) _Pragma("unroll") for (int k = 0; k < 2; ++k) \
;         acc[ai][bj][m][n] = __builtin_amdgcn_mfma_f32_16x16x32_bf16(Bt[n][k], At[m][k], acc[ai][bj][m][n], 0, 0, 0); __builtin_amdgcn_s_setprio(0); } while (0)
; #define PG8_WAIT_V(n) asm volatile("s_waitcnt vmcnt(" #n ")" ::: "memory")
; template <class Epi, class Sched>
; __device__ __forceinline__ void gemm_phase(PG8_LAS unsigned char* lds, const Gemm g, const Sched& S, const Epi& E) {
;     ...
;         for (int t = 0; t < nt; t += 2) {
;             const bool last = (t == nt - 2);
;             const char* a1 = cA + (size_t)(t + 1) * kstep;
;             const char* a2 = last ? nA : cA + (size_t)(t + 2) * kstep; const char* b2 = last ? nB : cB + (size_t)(t + 2) * kstep;
;             const char* a3 = a2 + kstep; const char* b3 = b2 + kstep;
;             if (last && has_next) S.a_ready(nxt);
;             PG8_LDB(B0, 0, 0); PG8_SCHED; PG8_LDA(At, 0, 0); PG8_STAGE(PG8_SA(1, 1), a1 + hstep, voffA);
;             PG8_WAIT_L(8); PG8_BAR; PG8_WAIT_L(0); PG8_MMA(0, 0, At, B0); PG8_BAR; PG8_SCHED;
;             PG8_LDB(B1, 0, 1); PG8_STAGE(PG8_SB(0, 0), b2, voffB);
;             PG8_BAR; PG8_WAIT_L(0); PG8_MMA(0, 1, At, B1); PG8_BAR;
;             PG8_LDA(At, 0, 1); PG8_STAGE(PG8_SA(0, 0), a2, voffA);
;             PG8_BAR; PG8_WAIT_L(0); PG8_MMA(1, 0, At, B0); PG8_BAR; PG8_SCHED;
;             PG8_STAGE(PG8_SB(0, 1), b2 + hstep, voffB);
;             PG8_WAIT_V(6); PG8_BAR; PG8_MMA(1, 1, At, B1); PG8_BAR;
.LBB0_1106:
	s_add_i32 s41, s12, 2
	s_add_u32 s14, s10, 0x80
	s_addc_u32 s13, s11, 0
	s_add_i32 s44, 0, 0x10000
	v_add_u32_e32 v137, s44, v151
	ds_read_b128 v[144:147], v137
	ds_read_b128 v[154:157], v137 offset:1024
	ds_read_b128 v[176:179], v137 offset:2048
	ds_read_b128 v[180:183], v137 offset:3072
	s_cmp_eq_u32 s31, s12
	s_cselect_b32 s12, s0, s14
	s_cselect_b32 s13, s1, s13
	s_cselect_b32 s15, s7, s40
	s_cselect_b32 s14, s6, s39
	v_lshl_add_u64 v[148:149], s[10:11], 0, v[140:141]
	s_add_i32 m0, s22, 0xc000
	ds_read_b128 v[184:187], v153
	ds_read_b128 v[188:191], v153 offset:1024
	ds_read_b128 v[192:195], v153 offset:2048
	ds_read_b128 v[196:199], v153 offset:3072
	ds_read_b128 v[200:203], v153 offset:4096
	ds_read_b128 v[204:207], v153 offset:5120
	ds_read_b128 v[208:211], v153 offset:6144
	ds_read_b128 v[212:215], v153 offset:7168
	global_load_lds_dwordx4 v[148:149], off
	v_lshl_add_u64 v[148:149], s[10:11], 0, v[142:143]
	s_add_i32 m0, s22, 0xe000
	s_nop 0
	global_load_lds_dwordx4 v[148:149], off
	s_waitcnt lgkmcnt(8)
	s_barrier
	s_waitcnt lgkmcnt(0)
	s_setprio 1
	s_waitcnt lgkmcnt(0)
	v_mfma_f32_16x16x32_bf16 v[126:129], v[144:147], v[184:187], v[126:129]
	v_mfma_f32_16x16x32_bf16 v[122:125], v[176:179], v[184:187], v[122:125]
	v_mfma_f32_16x16x32_bf16 v[110:113], v[144:147], v[192:195], v[110:113]
	v_mfma_f32_16x16x32_bf16 v[106:109], v[176:179], v[192:195], v[106:109]
	v_mfma_f32_16x16x32_bf16 v[94:97], v[144:147], v[200:203], v[94:97]
	v_mfma_f32_16x16x32_bf16 v[90:93], v[176:179], v[200:203], v[90:93]
	v_mfma_f32_16x16x32_bf16 v[78:81], v[144:147], v[208:211], v[78:81]
	v_mfma_f32_16x16x32_bf16 v[74:77], v[176:179], v[208:211], v[74:77]
	v_mfma_f32_16x16x32_bf16 v[126:129], v[154:157], v[188:191], v[126:129]
	v_mfma_f32_16x16x32_bf16 v[122:125], v[180:183], v[188:191], v[122:125]
	v_mfma_f32_16x16x32_bf16 v[110:113], v[154:157], v[196:199], v[110:113]
	v_mfma_f32_16x16x32_bf16 v[106:109], v[180:183], v[196:199], v[106:109]
	v_mfma_f32_16x16x32_bf16 v[94:97], v[154:157], v[204:207], v[94:97]
	v_mfma_f32_16x16x32_bf16 v[90:93], v[180:183], v[204:207], v[90:93]
	v_mfma_f32_16x16x32_bf16 v[78:81], v[154:157], v[212:215], v[78:81]
	v_mfma_f32_16x16x32_bf16 v[74:77], v[180:183], v[212:215], v[74:77]
	s_setprio 0
	s_barrier
	s_add_i32 s45, 0, 0x14000
	s_add_i32 s44, s44, s17
	v_add_u32_e32 v137, s45, v151
	v_lshl_add_u64 v[148:149], s[14:15], 0, v[0:1]
	s_mov_b32 m0, s44
	ds_read_b128 v[216:219], v137
	ds_read_b128 v[220:223], v137 offset:1024
	ds_read_b128 v[224:227], v137 offset:2048
	ds_read_b128 v[228:231], v137 offset:3072
	global_load_lds_dwordx4 v[148:149], off
	v_lshl_add_u64 v[158:159], s[14:15], 0, v[134:135]
	s_add_i32 m0, s44, 0x2000
	s_nop 0
	global_load_lds_dwordx4 v[158:159], off
	s_barrier
	s_waitcnt lgkmcnt(0)
	s_setprio 1
	s_waitcnt lgkmcnt(0)
	v_mfma_f32_16x16x32_bf16 v[118:121], v[216:219], v[184:187], v[118:121]
	v_mfma_f32_16x16x32_bf16 v[114:117], v[224:227], v[184:187], v[114:117]
	v_mfma_f32_16x16x32_bf16 v[102:105], v[216:219], v[192:195], v[102:105]
	v_mfma_f32_16x16x32_bf16 v[98:101], v[224:227], v[192:195], v[98:101]
	v_mfma_f32_16x16x32_bf16 v[86:89], v[216:219], v[200:203], v[86:89]
	v_mfma_f32_16x16x32_bf16 v[82:85], v[224:227], v[200:203], v[82:85]
	v_mfma_f32_16x16x32_bf16 v[70:73], v[216:219], v[208:211], v[70:73]
	v_mfma_f32_16x16x32_bf16 v[66:69], v[224:227], v[208:211], v[66:69]
	v_mfma_f32_16x16x32_bf16 v[118:121], v[220:223], v[188:191], v[118:121]
	v_mfma_f32_16x16x32_bf16 v[114:117], v[228:231], v[188:191], v[114:117]
	v_mfma_f32_16x16x32_bf16 v[102:105], v[220:223], v[196:199], v[102:105]
	v_mfma_f32_16x16x32_bf16 v[98:101], v[228:231], v[196:199], v[98:101]
	v_mfma_f32_16x16x32_bf16 v[86:89], v[220:223], v[204:207], v[86:89]
	v_mfma_f32_16x16x32_bf16 v[82:85], v[228:231], v[204:207], v[82:85]
	v_mfma_f32_16x16x32_bf16 v[70:73], v[220:223], v[212:215], v[70:73]
	v_mfma_f32_16x16x32_bf16 v[66:69], v[228:231], v[212:215], v[66:69]
	s_setprio 0
	s_mov_b32 m0, s22
	v_lshl_add_u64 v[232:233], s[12:13], 0, v[0:1]
	s_barrier
	ds_read_b128 v[184:187], v153 offset:16384
	ds_read_b128 v[188:191], v153 offset:17408
	ds_read_b128 v[192:195], v153 offset:18432
	ds_read_b128 v[196:199], v153 offset:19456
	ds_read_b128 v[200:203], v153 offset:20480
	ds_read_b128 v[204:207], v153 offset:21504
	ds_read_b128 v[208:211], v153 offset:22528
	ds_read_b128 v[212:215], v153 offset:23552
	global_load_lds_dwordx4 v[232:233], off
	v_lshl_add_u64 v[234:235], s[12:13], 0, v[134:135]
	s_mov_b32 m0, s23
	s_nop 0
	global_load_lds_dwordx4 v[234:235], off
	s_barrier
	s_waitcnt lgkmcnt(0)
	s_setprio 1
	s_waitcnt lgkmcnt(0)
	v_mfma_f32_16x16x32_bf16 v[62:65], v[144:147], v[184:187], v[62:65]
	v_mfma_f32_16x16x32_bf16 v[58:61], v[176:179], v[184:187], v[58:61]
	v_mfma_f32_16x16x32_bf16 v[46:49], v[144:147], v[192:195], v[46:49]
	v_mfma_f32_16x16x32_bf16 v[42:45], v[176:179], v[192:195], v[42:45]
	v_mfma_f32_16x16x32_bf16 v[30:33], v[144:147], v[200:203], v[30:33]
	v_mfma_f32_16x16x32_bf16 v[26:29], v[176:179], v[200:203], v[26:29]
	v_mfma_f32_16x16x32_bf16 v[14:17], v[144:147], v[208:211], v[14:17]
	v_mfma_f32_16x16x32_bf16 v[10:13], v[176:179], v[208:211], v[10:13]
	v_mfma_f32_16x16x32_bf16 v[62:65], v[154:157], v[188:191], v[62:65]
	v_mfma_f32_16x16x32_bf16 v[58:61], v[180:183], v[188:191], v[58:61]
	v_mfma_f32_16x16x32_bf16 v[46:49], v[154:157], v[196:199], v[46:49]
	v_mfma_f32_16x16x32_bf16 v[42:45], v[180:183], v[196:199], v[42:45]
	v_mfma_f32_16x16x32_bf16 v[30:33], v[154:157], v[204:207], v[30:33]
	v_mfma_f32_16x16x32_bf16 v[26:29], v[180:183], v[204:207], v[26:29]
	v_mfma_f32_16x16x32_bf16 v[14:17], v[154:157], v[212:215], v[14:17]
	v_mfma_f32_16x16x32_bf16 v[10:13], v[180:183], v[212:215], v[10:13]
	s_setprio 0
	s_barrier
; #define PG8_STAGE(bufoff, gbase, voff) do { _Pragma("unroll") for (int _i = 0; _i < 2; ++_i) \
;         __builtin_amdgcn_global_load_lds((const unsigned*)((const char*)(gbase) + (voff)[_i]), (PG8_LAS unsigned*)(lds + (bufoff) + ldsw + _i * 8192), 16, 0, 0); } while (0)
; #define PG8_LDA(dst, b, h) do { _Pragma("unroll") for (int m = 0; m < 4; ++m) _Pragma("unroll") for (int k = 0; k < 2; ++k) dst[m][k] = *(const PG8_LAS bf16x8*)(lds + PG8_SA(b, h) + aoff + m * 2048 + k * 1024); } while (0)
; #define PG8_LDB(dst, b, h) do { _Pragma("unroll") for (int n = 0; n < 2; ++n) _Pragma("unroll") for (int k = 0; k < 2; ++k) dst[n][k] = *(const PG8_LAS bf16x8*)(lds + PG8_SB(b, h) + boff + n * 2048 + k * 1024); } while (0)
; #define PG8_MMA(ai, bj, At, Bt) do { __builtin_amdgcn_s_setprio(1); _Pragma("unroll") for (int m = 0; m < 4; ++m) _Pragma("unroll") for (int n = 0; n < 2; ++n) _Pragma("unroll") for (int k = 0; k < 2; ++k) \
;         acc[ai][bj][m][n] = __builtin_amdgcn_mfma_f32_16x16x32_bf16(Bt[n][k], At[m][k], acc[ai][bj][m][n], 0, 0, 0); __builtin_amdgcn_s_setprio(0); } while (0)
; #define PG8_WAIT_V(n) asm volatile("s_waitcnt vmcnt(" #n ")" ::: "memory")
; #define PG8_WAIT_L(n) asm volatile("s_waitcnt lgkmcnt(" #n ")" ::: "memory")
; #define PG8_BAR __builtin_amdgcn_s_barrier()
; #define PG8_SCHED __builtin_amdgcn_sched_barrier(0)
; template <class Epi, class Sched>
; __device__ __forceinline__ void gemm_phase(PG8_LAS unsigned char* lds, const Gemm g, const Sched& S, const Epi& E) {
;     ...
;             PG8_STAGE(PG8_SB(0, 1), b2 + hstep, voffB);
;             PG8_WAIT_V(6); PG8_BAR; PG8_MMA(1, 1, At, B1); PG8_BAR;
;             PG8_LDB(B0, 1, 0); PG8_SCHED; PG8_LDA(At, 1, 0); PG8_STAGE(PG8_SA(0, 1), a2 + hstep, voffA);
;             PG8_WAIT_L(8); PG8_BAR; PG8_WAIT_L(0); PG8_MMA(0, 0, At, B0); PG8_BAR; PG8_SCHED;
;             PG8_LDB(B1, 1, 1); PG8_STAGE(PG8_SB(1, 0), b3, voffB);
;             PG8_BAR; PG8_WAIT_L(0); PG8_MMA(0, 1, At, B1); PG8_BAR;
;             PG8_LDA(At, 1, 1); PG8_STAGE(PG8_SA(1, 0), a3, voffA);
;             PG8_BAR; PG8_WAIT_L(0); PG8_MMA(1, 0, At, B0); PG8_BAR; PG8_SCHED;
	s_add_u32 s14, s14, s72
	s_addc_u32 s15, s15, 0
	s_add_i32 s44, s45, s17
	v_lshl_add_u64 v[236:237], s[14:15], 0, v[0:1]
	s_mov_b32 m0, s44
	v_lshl_add_u64 v[238:239], s[14:15], 0, v[134:135]
	global_load_lds_dwordx4 v[236:237], off
	s_add_i32 m0, s44, 0x2000
	s_nop 0
	global_load_lds_dwordx4 v[238:239], off
	s_waitcnt vmcnt(6)
	s_barrier
	s_setprio 1
	v_mfma_f32_16x16x32_bf16 v[54:57], v[216:219], v[184:187], v[54:57]
	v_mfma_f32_16x16x32_bf16 v[50:53], v[224:227], v[184:187], v[50:53]
	v_mfma_f32_16x16x32_bf16 v[38:41], v[216:219], v[192:195], v[38:41]
	v_mfma_f32_16x16x32_bf16 v[34:37], v[224:227], v[192:195], v[34:37]
	v_mfma_f32_16x16x32_bf16 v[22:25], v[216:219], v[200:203], v[22:25]
	v_mfma_f32_16x16x32_bf16 v[18:21], v[224:227], v[200:203], v[18:21]
	v_mfma_f32_16x16x32_bf16 v[6:9], v[216:219], v[208:211], v[6:9]
	v_mfma_f32_16x16x32_bf16 v[2:5], v[224:227], v[208:211], v[2:5]
	v_mfma_f32_16x16x32_bf16 v[54:57], v[220:223], v[188:191], v[54:57]
	v_mfma_f32_16x16x32_bf16 v[50:53], v[228:231], v[188:191], v[50:53]
	v_mfma_f32_16x16x32_bf16 v[38:41], v[220:223], v[196:199], v[38:41]
	v_mfma_f32_16x16x32_bf16 v[34:37], v[228:231], v[196:199], v[34:37]
	v_mfma_f32_16x16x32_bf16 v[22:25], v[220:223], v[204:207], v[22:25]
	v_mfma_f32_16x16x32_bf16 v[18:21], v[228:231], v[204:207], v[18:21]
	v_mfma_f32_16x16x32_bf16 v[6:9], v[220:223], v[212:215], v[6:9]
	v_mfma_f32_16x16x32_bf16 v[2:5], v[228:231], v[212:215], v[2:5]
	s_setprio 0
	s_add_i32 s14, 0, 0x18000
	v_add_u32_e32 v137, s14, v151
	s_barrier
	ds_read_b128 v[144:147], v137
	ds_read_b128 v[154:157], v137 offset:1024
	ds_read_b128 v[176:179], v137 offset:2048
	ds_read_b128 v[180:183], v137 offset:3072
	s_add_u32 s12, s12, s72
	s_addc_u32 s13, s13, 0
	s_mov_b32 m0, s26
	v_lshl_add_u64 v[216:217], s[12:13], 0, v[0:1]
	ds_read_b128 v[184:187], v153 offset:32768
	ds_read_b128 v[188:191], v153 offset:33792
	ds_read_b128 v[192:195], v153 offset:34816
	ds_read_b128 v[196:199], v153 offset:35840
	ds_read_b128 v[200:203], v153 offset:36864
	ds_read_b128 v[204:207], v153 offset:37888
	ds_read_b128 v[208:211], v153 offset:38912
	ds_read_b128 v[212:215], v153 offset:39936
	global_load_lds_dwordx4 v[216:217], off
	v_lshl_add_u64 v[216:217], s[12:13], 0, v[134:135]
	s_mov_b32 m0, s27
	s_nop 0
	global_load_lds_dwordx4 v[216:217], off
	s_waitcnt lgkmcnt(8)
	s_barrier
	s_waitcnt lgkmcnt(0)
	s_setprio 1
	s_waitcnt lgkmcnt(0)
	v_mfma_f32_16x16x32_bf16 v[126:129], v[144:147], v[184:187], v[126:129]
	v_mfma_f32_16x16x32_bf16 v[122:125], v[176:179], v[184:187], v[122:125]
	v_mfma_f32_16x16x32_bf16 v[110:113], v[144:147], v[192:195], v[110:113]
	v_mfma_f32_16x16x32_bf16 v[106:109], v[176:179], v[192:195], v[106:109]
	v_mfma_f32_16x16x32_bf16 v[94:97], v[144:147], v[200:203], v[94:97]
	v_mfma_f32_16x16x32_bf16 v[90:93], v[176:179], v[200:203], v[90:93]
	v_mfma_f32_16x16x32_bf16 v[78:81], v[144:147], v[208:211], v[78:81]
	v_mfma_f32_16x16x32_bf16 v[74:77], v[176:179], v[208:211], v[74:77]
	v_mfma_f32_16x16x32_bf16 v[126:129], v[154:157], v[188:191], v[126:129]
	v_mfma_f32_16x16x32_bf16 v[122:125], v[180:183], v[188:191], v[122:125]
	v_mfma_f32_16x16x32_bf16 v[110:113], v[154:157], v[196:199], v[110:113]
	v_mfma_f32_16x16x32_bf16 v[106:109], v[180:183], v[196:199], v[106:109]
	v_mfma_f32_16x16x32_bf16 v[94:97], v[154:157], v[204:207], v[94:97]
	v_mfma_f32_16x16x32_bf16 v[90:93], v[180:183], v[204:207], v[90:93]
	v_mfma_f32_16x16x32_bf16 v[78:81], v[154:157], v[212:215], v[78:81]
	v_mfma_f32_16x16x32_bf16 v[74:77], v[180:183], v[212:215], v[74:77]
	s_setprio 0
	s_barrier
	s_add_i32 s12, 0, 0x1c000
	s_add_i32 s13, s14, s17
	v_add_u32_e32 v137, s12, v151
	v_lshl_add_u64 v[148:149], v[148:149], 0, s[70:71]
	s_mov_b32 m0, s13
	ds_read_b128 v[216:219], v137
	ds_read_b128 v[220:223], v137 offset:1024
	ds_read_b128 v[224:227], v137 offset:2048
	ds_read_b128 v[228:231], v137 offset:3072
	global_load_lds_dwordx4 v[148:149], off
	v_lshl_add_u64 v[148:149], v[158:159], 0, s[70:71]
	s_add_i32 m0, s13, 0x2000
	s_nop 0
	global_load_lds_dwordx4 v[148:149], off
	s_barrier
	s_waitcnt lgkmcnt(0)
	s_setprio 1
	s_waitcnt lgkmcnt(0)
	v_mfma_f32_16x16x32_bf16 v[118:121], v[216:219], v[184:187], v[118:121]
	v_mfma_f32_16x16x32_bf16 v[114:117], v[224:227], v[184:187], v[114:117]
	v_mfma_f32_16x16x32_bf16 v[102:105], v[216:219], v[192:195], v[102:105]
	v_mfma_f32_16x16x32_bf16 v[98:101], v[224:227], v[192:195], v[98:101]
	v_mfma_f32_16x16x32_bf16 v[86:89], v[216:219], v[200:203], v[86:89]
	v_mfma_f32_16x16x32_bf16 v[82:85], v[224:227], v[200:203], v[82:85]
	v_mfma_f32_16x16x32_bf16 v[70:73], v[216:219], v[208:211], v[70:73]
	v_mfma_f32_16x16x32_bf16 v[66:69], v[224:227], v[208:211], v[66:69]
	v_mfma_f32_16x16x32_bf16 v[118:121], v[220:223], v[188:191], v[118:121]
	v_mfma_f32_16x16x32_bf16 v[114:117], v[228:231], v[188:191], v[114:117]
	v_mfma_f32_16x16x32_bf16 v[102:105], v[220:223], v[196:199], v[102:105]
	v_mfma_f32_16x16x32_bf16 v[98:101], v[228:231], v[196:199], v[98:101]
	v_mfma_f32_16x16x32_bf16 v[86:89], v[220:223], v[204:207], v[86:89]
	v_mfma_f32_16x16x32_bf16 v[82:85], v[228:231], v[204:207], v[82:85]
	v_mfma_f32_16x16x32_bf16 v[70:73], v[220:223], v[212:215], v[70:73]
	v_mfma_f32_16x16x32_bf16 v[66:69], v[228:231], v[212:215], v[66:69]
	s_setprio 0
	s_mov_b32 m0, s28
	v_lshl_add_u64 v[148:149], v[232:233], 0, s[70:71]
	s_barrier
	ds_read_b128 v[184:187], v153 offset:49152
	ds_read_b128 v[188:191], v153 offset:50176
	ds_read_b128 v[192:195], v153 offset:51200
	ds_read_b128 v[196:199], v153 offset:52224
	ds_read_b128 v[200:203], v153 offset:53248
	ds_read_b128 v[204:207], v153 offset:54272
	ds_read_b128 v[208:211], v153 offset:55296
	ds_read_b128 v[212:215], v153 offset:56320
	global_load_lds_dwordx4 v[148:149], off
	v_lshl_add_u64 v[148:149], v[234:235], 0, s[70:71]
	s_mov_b32 m0, s29
	s_nop 0
	global_load_lds_dwordx4 v[148:149], off
	s_barrier
; #define PG8_STAGE(bufoff, gbase, voff) do { _Pragma("unroll") for (int _i = 0; _i < 2; ++_i) \
;         __builtin_amdgcn_global_load_lds((const unsigned*)((const char*)(gbase) + (voff)[_i]), (PG8_LAS unsigned*)(lds + (bufoff) + ldsw + _i * 8192), 16, 0, 0); } while (0)
; #define PG8_MMA(ai, bj, At, Bt) do { __builtin_amdgcn_s_setprio(1); _Pragma("unroll") for (int m = 0; m < 4; ++m) _Pragma("unroll") for (int n = 0; n < 2; ++n) _Pragma("unroll") for (int k = 0; k < 2; ++k) \
;         acc[ai][bj][m][n] = __builtin_amdgcn_mfma_f32_16x16x32_bf16(Bt[n][k], At[m][k], acc[ai][bj][m][n], 0, 0, 0); __builtin_amdgcn_s_setprio(0); } while (0)
; #define PG8_WAIT_V(n) asm volatile("s_waitcnt vmcnt(" #n ")" ::: "memory")
; #define PG8_WAIT_L(n) asm volatile("s_waitcnt lgkmcnt(" #n ")" ::: "memory")
; #define PG8_BAR __builtin_amdgcn_s_barrier()
; #define PG8_SCHED __builtin_amdgcn_sched_barrier(0)
; template <class Epi, class Sched>
; __device__ __forceinline__ void gemm_phase(PG8_LAS unsigned char* lds, const Gemm g, const Sched& S, const Epi& E) {
;     ...
;             PG8_BAR; PG8_WAIT_L(0); PG8_MMA(1, 0, At, B0); PG8_BAR; PG8_SCHED;
;             PG8_STAGE(PG8_SB(1, 1), b3 + hstep, voffB);
;             PG8_WAIT_V(6); PG8_BAR; PG8_MMA(1, 1, At, B1); PG8_BAR;
;         }
;         if constexpr (!Epi::AFTER_DRAIN) { E(acc, cur, wr, wc, fr, fq); S.done(cur); }
;     __device__ __forceinline__ void operator()(const f32x4 (&acc)[2][2][4][2], const pg8::Unit& u, int wr, int wc, int fr, int fq) const {
;         const int row0 = u.pm * 256 + wr * 64 + fr, col0 = u.pn * 256 + wc * 32 + 4 * fq;
; #pragma unroll
;         for (int ai = 0; ai < 2; ++ai)
; #pragma unroll
;             for (int m = 0; m < 4; ++m) {
;                 const size_t ro = (size_t)(row0 + ai * 128 + m * 16) * D + col0;
; #pragma unroll
;                 for (int bj = 0; bj < 2; ++bj)
; #pragma unroll
;                     for (int n = 0; n < 2; ++n) { const size_t o = ro + bj * 128 + n * 16; *(f32x4*)(X + o) = *(const f32x4*)(Xs + o) + acc[ai][bj][m][n] * scale; }
;             }
;     }
	s_waitcnt lgkmcnt(0)
	s_setprio 1
	s_waitcnt lgkmcnt(0)
	v_mfma_f32_16x16x32_bf16 v[62:65], v[144:147], v[184:187], v[62:65]
	v_mfma_f32_16x16x32_bf16 v[58:61], v[176:179], v[184:187], v[58:61]
	v_mfma_f32_16x16x32_bf16 v[46:49], v[144:147], v[192:195], v[46:49]
	v_mfma_f32_16x16x32_bf16 v[42:45], v[176:179], v[192:195], v[42:45]
	v_mfma_f32_16x16x32_bf16 v[30:33], v[144:147], v[200:203], v[30:33]
	v_mfma_f32_16x16x32_bf16 v[26:29], v[176:179], v[200:203], v[26:29]
	v_mfma_f32_16x16x32_bf16 v[14:17], v[144:147], v[208:211], v[14:17]
	v_mfma_f32_16x16x32_bf16 v[10:13], v[176:179], v[208:211], v[10:13]
	v_mfma_f32_16x16x32_bf16 v[62:65], v[154:157], v[188:191], v[62:65]
	v_mfma_f32_16x16x32_bf16 v[58:61], v[180:183], v[188:191], v[58:61]
	v_mfma_f32_16x16x32_bf16 v[46:49], v[154:157], v[196:199], v[46:49]
	v_mfma_f32_16x16x32_bf16 v[42:45], v[180:183], v[196:199], v[42:45]
	v_mfma_f32_16x16x32_bf16 v[30:33], v[154:157], v[204:207], v[30:33]
	v_mfma_f32_16x16x32_bf16 v[26:29], v[180:183], v[204:207], v[26:29]
	v_mfma_f32_16x16x32_bf16 v[14:17], v[154:157], v[212:215], v[14:17]
	v_mfma_f32_16x16x32_bf16 v[10:13], v[180:183], v[212:215], v[10:13]
	s_setprio 0
	s_barrier
	s_add_i32 s12, s12, s17
	v_lshl_add_u64 v[144:145], v[236:237], 0, s[70:71]
	s_mov_b32 m0, s12
	s_nop 0
	global_load_lds_dwordx4 v[144:145], off
	v_lshl_add_u64 v[144:145], v[238:239], 0, s[70:71]
	s_add_i32 m0, s12, 0x2000
	s_nop 0
	global_load_lds_dwordx4 v[144:145], off
	s_waitcnt vmcnt(6)
	s_barrier
	s_setprio 1
	v_mfma_f32_16x16x32_bf16 v[54:57], v[216:219], v[184:187], v[54:57]
	v_mfma_f32_16x16x32_bf16 v[50:53], v[224:227], v[184:187], v[50:53]
	v_mfma_f32_16x16x32_bf16 v[38:41], v[216:219], v[192:195], v[38:41]
	v_mfma_f32_16x16x32_bf16 v[34:37], v[224:227], v[192:195], v[34:37]
	v_mfma_f32_16x16x32_bf16 v[22:25], v[216:219], v[200:203], v[22:25]
	v_mfma_f32_16x16x32_bf16 v[18:21], v[224:227], v[200:203], v[18:21]
	v_mfma_f32_16x16x32_bf16 v[6:9], v[216:219], v[208:211], v[6:9]
	v_mfma_f32_16x16x32_bf16 v[2:5], v[224:227], v[208:211], v[2:5]
	v_mfma_f32_16x16x32_bf16 v[54:57], v[220:223], v[188:191], v[54:57]
	v_mfma_f32_16x16x32_bf16 v[50:53], v[228:231], v[188:191], v[50:53]
	v_mfma_f32_16x16x32_bf16 v[38:41], v[220:223], v[196:199], v[38:41]
	v_mfma_f32_16x16x32_bf16 v[34:37], v[228:231], v[196:199], v[34:37]
	v_mfma_f32_16x16x32_bf16 v[22:25], v[220:223], v[204:207], v[22:25]
	v_mfma_f32_16x16x32_bf16 v[18:21], v[228:231], v[204:207], v[18:21]
	v_mfma_f32_16x16x32_bf16 v[6:9], v[220:223], v[212:215], v[6:9]
	v_mfma_f32_16x16x32_bf16 v[2:5], v[228:231], v[212:215], v[2:5]
	s_setprio 0
	s_add_u32 s10, s10, 0x100
	s_addc_u32 s11, s11, 0
	s_add_u32 s39, s39, 0x100
	s_addc_u32 s40, s40, 0
	s_cmp_ge_u32 s41, s30
	s_mov_b32 s12, s41
	s_barrier
	s_cbranch_scc0 .LBB0_1106
	v_lshl_add_u32 v148, s38, 8, v150
	v_lshl_or_b32 v146, s37, 8, v152
	v_lshl_add_u32 v208, v148, 10, v146
	v_mov_b32_e32 v137, v136
	s_and_b64 vcc, exec, s[4:5]
	s_mov_b32 s37, s35
	s_mov_b32 s38, s36
	s_mov_b64 s[12:13], s[6:7]
	s_mov_b64 s[10:11], s[0:1]
	v_lshlrev_b32_e32 v208, 2, v208
	v_add_u32_e32 v209, 0x10000, v208
	v_add_u32_e32 v210, 0x20000, v208
	v_add_u32_e32 v211, 0x30000, v208
	v_add_u32_e32 v212, 0x80000, v208
	v_add_u32_e32 v213, 0x90000, v208
	v_add_u32_e32 v214, 0xa0000, v208
	v_add_u32_e32 v215, 0xb0000, v208
	global_load_dwordx4 v[176:179], v208, s[8:9]
	global_load_dwordx4 v[180:183], v208, s[8:9] offset:64
	global_load_dwordx4 v[184:187], v208, s[8:9] offset:512
	global_load_dwordx4 v[188:191], v208, s[8:9] offset:576
	global_load_dwordx4 v[192:195], v209, s[8:9]
	global_load_dwordx4 v[196:199], v209, s[8:9] offset:64
	global_load_dwordx4 v[200:203], v209, s[8:9] offset:512
	global_load_dwordx4 v[204:207], v209, s[8:9] offset:576
	s_waitcnt vmcnt(7)
	v_pk_fma_f32 v[128:129], v[136:137], v[128:129], v[178:179]
	v_pk_fma_f32 v[126:127], v[138:139], v[126:127], v[176:177]
	global_store_dwordx4 v208, v[126:129], s[92:93] sc1
	s_waitcnt vmcnt(7)
	v_pk_fma_f32 v[124:125], v[136:137], v[124:125], v[182:183]
	v_pk_fma_f32 v[122:123], v[138:139], v[122:123], v[180:181]
	global_store_dwordx4 v208, v[122:125], s[92:93] offset:64 sc1
	s_waitcnt vmcnt(7)
	v_pk_fma_f32 v[120:121], v[136:137], v[120:121], v[186:187]
	v_pk_fma_f32 v[118:119], v[138:139], v[118:119], v[184:185]
	global_store_dwordx4 v208, v[118:121], s[92:93] offset:512 sc1
	s_waitcnt vmcnt(7)
	v_pk_fma_f32 v[116:117], v[136:137], v[116:117], v[190:191]
	v_pk_fma_f32 v[114:115], v[138:139], v[114:115], v[188:189]
	global_store_dwordx4 v208, v[114:117], s[92:93] offset:576 sc1
	global_load_dwordx4 v[176:179], v210, s[8:9]
	global_load_dwordx4 v[180:183], v210, s[8:9] offset:64
	global_load_dwordx4 v[184:187], v210, s[8:9] offset:512
	global_load_dwordx4 v[188:191], v210, s[8:9] offset:576
	s_waitcnt vmcnt(11)
	v_pk_fma_f32 v[112:113], v[136:137], v[112:113], v[194:195]
	v_pk_fma_f32 v[110:111], v[138:139], v[110:111], v[192:193]
	global_store_dwordx4 v209, v[110:113], s[92:93] sc1
	s_waitcnt vmcnt(11)
	v_pk_fma_f32 v[108:109], v[136:137], v[108:109], v[198:199]
	v_pk_fma_f32 v[106:107], v[138:139], v[106:107], v[196:197]
	global_store_dwordx4 v209, v[106:109], s[92:93] offset:64 sc1
	s_waitcnt vmcnt(11)
	v_pk_fma_f32 v[104:105], v[136:137], v[104:105], v[202:203]
	v_pk_fma_f32 v[102:103], v[138:139], v[102:103], v[200:201]
	global_store_dwordx4 v209, v[102:105], s[92:93] offset:512 sc1
	s_waitcnt vmcnt(11)
	v_pk_fma_f32 v[100:101], v[136:137], v[100:101], v[206:207]
	v_pk_fma_f32 v[98:99], v[138:139], v[98:99], v[204:205]
	global_store_dwordx4 v209, v[98:101], s[92:93] offset:576 sc1
	global_load_dwordx4 v[192:195], v211, s[8:9]
	global_load_dwordx4 v[196:199], v211, s[8:9] offset:64
	global_load_dwordx4 v[200:203], v211, s[8:9] offset:512
	global_load_dwordx4 v[204:207], v211, s[8:9] offset:576
	s_waitcnt vmcnt(11)
; #define PG8_WAIT_V(n) asm volatile("s_waitcnt vmcnt(" #n ")" ::: "memory")
; #define PG8_BAR __builtin_amdgcn_s_barrier()
; template <class Epi, class Sched>
; __device__ __forceinline__ void gemm_phase(PG8_LAS unsigned char* lds, const Gemm g, const Sched& S, const Epi& E) {
;     ...
;         if (!has_next) break;
; #pragma unroll
;         for (int a = 0; a < 2; ++a)
; #pragma unroll
;             for (int b = 0; b < 2; ++b)
; #pragma unroll
;                 for (int m = 0; m < 4; ++m)
; #pragma unroll
;                     for (int n = 0; n < 2; ++n) acc[a][b][m][n] = (f32x4){0.f, 0.f, 0.f, 0.f};
;         cur = nxt; cA = nA; cB = nB; ++ui;
;     }
;     PG8_WAIT_V(0);
;     if (wr == 0) PG8_BAR;
;     PG8_BAR;
;     __device__ __forceinline__ void operator()(const f32x4 (&acc)[2][2][4][2], const pg8::Unit& u, int wr, int wc, int fr, int fq) const {
;         const int row0 = u.pm * 256 + wr * 64 + fr, col0 = u.pn * 256 + wc * 32 + 4 * fq;
; #pragma unroll
;         for (int ai = 0; ai < 2; ++ai)
; #pragma unroll
;             for (int m = 0; m < 4; ++m) {
;                 const size_t ro = (size_t)(row0 + ai * 128 + m * 16) * D + col0;
; #pragma unroll
;                 for (int bj = 0; bj < 2; ++bj)
; #pragma unroll
;                     for (int n = 0; n < 2; ++n) { const size_t o = ro + bj * 128 + n * 16; *(f32x4*)(X + o) = *(const f32x4*)(Xs + o) + acc[ai][bj][m][n] * scale; }
;             }
;     }
	v_pk_fma_f32 v[96:97], v[136:137], v[96:97], v[178:179]
	v_pk_fma_f32 v[94:95], v[138:139], v[94:95], v[176:177]
	global_store_dwordx4 v210, v[94:97], s[92:93] sc1
	s_waitcnt vmcnt(11)
	v_pk_fma_f32 v[92:93], v[136:137], v[92:93], v[182:183]
	v_pk_fma_f32 v[90:91], v[138:139], v[90:91], v[180:181]
	global_store_dwordx4 v210, v[90:93], s[92:93] offset:64 sc1
	s_waitcnt vmcnt(11)
	v_pk_fma_f32 v[88:89], v[136:137], v[88:89], v[186:187]
	v_pk_fma_f32 v[86:87], v[138:139], v[86:87], v[184:185]
	global_store_dwordx4 v210, v[86:89], s[92:93] offset:512 sc1
	s_waitcnt vmcnt(11)
	v_pk_fma_f32 v[84:85], v[136:137], v[84:85], v[190:191]
	v_pk_fma_f32 v[82:83], v[138:139], v[82:83], v[188:189]
	global_store_dwordx4 v210, v[82:85], s[92:93] offset:576 sc1
	global_load_dwordx4 v[176:179], v212, s[8:9]
	global_load_dwordx4 v[180:183], v212, s[8:9] offset:64
	global_load_dwordx4 v[184:187], v212, s[8:9] offset:512
	global_load_dwordx4 v[188:191], v212, s[8:9] offset:576
	s_waitcnt vmcnt(11)
	v_pk_fma_f32 v[80:81], v[136:137], v[80:81], v[194:195]
	v_pk_fma_f32 v[78:79], v[138:139], v[78:79], v[192:193]
	global_store_dwordx4 v211, v[78:81], s[92:93] sc1
	s_waitcnt vmcnt(11)
	v_pk_fma_f32 v[76:77], v[136:137], v[76:77], v[198:199]
	v_pk_fma_f32 v[74:75], v[138:139], v[74:75], v[196:197]
	global_store_dwordx4 v211, v[74:77], s[92:93] offset:64 sc1
	s_waitcnt vmcnt(11)
	v_pk_fma_f32 v[72:73], v[136:137], v[72:73], v[202:203]
	v_pk_fma_f32 v[70:71], v[138:139], v[70:71], v[200:201]
	global_store_dwordx4 v211, v[70:73], s[92:93] offset:512 sc1
	s_waitcnt vmcnt(11)
	v_pk_fma_f32 v[68:69], v[136:137], v[68:69], v[206:207]
	v_pk_fma_f32 v[66:67], v[138:139], v[66:67], v[204:205]
	global_store_dwordx4 v211, v[66:69], s[92:93] offset:576 sc1
	global_load_dwordx4 v[192:195], v213, s[8:9]
	global_load_dwordx4 v[196:199], v213, s[8:9] offset:64
	global_load_dwordx4 v[200:203], v213, s[8:9] offset:512
	global_load_dwordx4 v[204:207], v213, s[8:9] offset:576
	s_waitcnt vmcnt(11)
	v_pk_fma_f32 v[64:65], v[136:137], v[64:65], v[178:179]
	v_pk_fma_f32 v[62:63], v[138:139], v[62:63], v[176:177]
	global_store_dwordx4 v212, v[62:65], s[92:93] sc1
	s_waitcnt vmcnt(11)
	v_pk_fma_f32 v[60:61], v[136:137], v[60:61], v[182:183]
	v_pk_fma_f32 v[58:59], v[138:139], v[58:59], v[180:181]
	global_store_dwordx4 v212, v[58:61], s[92:93] offset:64 sc1
	s_waitcnt vmcnt(11)
	v_pk_fma_f32 v[56:57], v[136:137], v[56:57], v[186:187]
	v_pk_fma_f32 v[54:55], v[138:139], v[54:55], v[184:185]
	global_store_dwordx4 v212, v[54:57], s[92:93] offset:512 sc1
	s_waitcnt vmcnt(11)
	v_pk_fma_f32 v[52:53], v[136:137], v[52:53], v[190:191]
	v_pk_fma_f32 v[50:51], v[138:139], v[50:51], v[188:189]
	global_store_dwordx4 v212, v[50:53], s[92:93] offset:576 sc1
	global_load_dwordx4 v[176:179], v214, s[8:9]
	global_load_dwordx4 v[180:183], v214, s[8:9] offset:64
	global_load_dwordx4 v[184:187], v214, s[8:9] offset:512
	global_load_dwordx4 v[188:191], v214, s[8:9] offset:576
	s_waitcnt vmcnt(11)
	v_pk_fma_f32 v[48:49], v[136:137], v[48:49], v[194:195]
	v_pk_fma_f32 v[46:47], v[138:139], v[46:47], v[192:193]
	global_store_dwordx4 v213, v[46:49], s[92:93] sc1
	s_waitcnt vmcnt(11)
	v_pk_fma_f32 v[44:45], v[136:137], v[44:45], v[198:199]
	v_pk_fma_f32 v[42:43], v[138:139], v[42:43], v[196:197]
	global_store_dwordx4 v213, v[42:45], s[92:93] offset:64 sc1
	s_waitcnt vmcnt(11)
	v_pk_fma_f32 v[40:41], v[136:137], v[40:41], v[202:203]
	v_pk_fma_f32 v[38:39], v[138:139], v[38:39], v[200:201]
	global_store_dwordx4 v213, v[38:41], s[92:93] offset:512 sc1
	s_waitcnt vmcnt(11)
	v_pk_fma_f32 v[36:37], v[136:137], v[36:37], v[206:207]
	v_pk_fma_f32 v[34:35], v[138:139], v[34:35], v[204:205]
	global_store_dwordx4 v213, v[34:37], s[92:93] offset:576 sc1
	global_load_dwordx4 v[192:195], v215, s[8:9]
	global_load_dwordx4 v[196:199], v215, s[8:9] offset:64
	global_load_dwordx4 v[200:203], v215, s[8:9] offset:512
	global_load_dwordx4 v[204:207], v215, s[8:9] offset:576
	s_waitcnt vmcnt(11)
	v_pk_fma_f32 v[32:33], v[136:137], v[32:33], v[178:179]
	v_pk_fma_f32 v[30:31], v[138:139], v[30:31], v[176:177]
	global_store_dwordx4 v214, v[30:33], s[92:93] sc1
	s_waitcnt vmcnt(11)
	v_pk_fma_f32 v[28:29], v[136:137], v[28:29], v[182:183]
	v_pk_fma_f32 v[26:27], v[138:139], v[26:27], v[180:181]
	global_store_dwordx4 v214, v[26:29], s[92:93] offset:64 sc1
	s_waitcnt vmcnt(11)
	v_pk_fma_f32 v[24:25], v[136:137], v[24:25], v[186:187]
	v_pk_fma_f32 v[22:23], v[138:139], v[22:23], v[184:185]
	global_store_dwordx4 v214, v[22:25], s[92:93] offset:512 sc1
	s_waitcnt vmcnt(11)
	v_pk_fma_f32 v[20:21], v[136:137], v[20:21], v[190:191]
	v_pk_fma_f32 v[18:19], v[138:139], v[18:19], v[188:189]
	global_store_dwordx4 v214, v[18:21], s[92:93] offset:576 sc1
	s_waitcnt vmcnt(7)
	v_pk_fma_f32 v[16:17], v[136:137], v[16:17], v[194:195]
	v_pk_fma_f32 v[14:15], v[138:139], v[14:15], v[192:193]
	global_store_dwordx4 v215, v[14:17], s[92:93] sc1
	s_waitcnt vmcnt(7)
	v_pk_fma_f32 v[12:13], v[136:137], v[12:13], v[198:199]
	v_pk_fma_f32 v[10:11], v[138:139], v[10:11], v[196:197]
	global_store_dwordx4 v215, v[10:13], s[92:93] offset:64 sc1
	s_waitcnt vmcnt(7)
	v_pk_fma_f32 v[8:9], v[136:137], v[8:9], v[202:203]
	v_pk_fma_f32 v[6:7], v[138:139], v[6:7], v[200:201]
	global_store_dwordx4 v215, v[6:9], s[92:93] offset:512 sc1
	s_waitcnt vmcnt(7)
	v_pk_fma_f32 v[4:5], v[136:137], v[4:5], v[206:207]
	v_pk_fma_f32 v[2:3], v[138:139], v[2:3], v[204:205]
	global_store_dwordx4 v215, v[2:5], s[92:93] offset:576 sc1
	s_cbranch_vccz .LBB0_1095
	s_waitcnt vmcnt(0)
	s_cmpk_gt_u32 s2, 0xff
	s_cbranch_scc1 .LBB0_1110
	s_barrier

; #define PG8_STAGE(bufoff, gbase, voff) do { _Pragma("unroll") for (int _i = 0; _i < 2; ++_i) \
;         __builtin_amdgcn_global_load_lds((const unsigned*)((const char*)(gbase) + (voff)[_i]), (PG8_LAS unsigned*)(lds + (bufoff) + ldsw + _i * 8192), 16, 0, 0); } while (0)
; #define PG8_LDA(dst, b, h) do { _Pragma("unroll") for (int m = 0; m < 4; ++m) _Pragma("unroll") for (int k = 0; k < 2; ++k) dst[m][k] = *(const PG8_LAS bf16x8*)(lds + PG8_SA(b, h) + aoff + m * 2048 + k * 1024); } while (0)
; #define PG8_LDB(dst, b, h) do { _Pragma("unroll") for (int n = 0; n < 2; ++n) _Pragma("unroll") for (int k = 0; k < 2; ++k) dst[n][k] = *(const PG8_LAS bf16x8*)(lds + PG8_SB(b, h) + boff + n * 2048 + k * 1024); } while (0)
; #define PG8_MMA(ai, bj, At, Bt) do { __builtin_amdgcn_s_setprio(1); _Pragma("unroll") for (int m = 0; m < 4; ++m) _Pragma("unroll") for (int n = 0; n < 2; ++n) _Pragma("unroll") for (int k = 0; k < 2; ++k) \
;         acc[ai][bj][m][n] = __builtin_amdgcn_mfma_f32_16x16x32_bf16(Bt[n][k], At[m][k], acc[ai][bj][m][n], 0, 0, 0); __builtin_amdgcn_s_setprio(0); } while (0)
; #define PG8_WAIT_V(n) asm volatile("s_waitcnt vmcnt(" #n ")" ::: "memory")
; template <class Epi, class Sched>
; __device__ __forceinline__ void gemm_phase(PG8_LAS unsigned char* lds, const Gemm g, const Sched& S, const Epi& E) {
;     ...
;         for (int t = 0; t < nt; t += 2) {
;             const bool last = (t == nt - 2);
;             const char* a1 = cA + (size_t)(t + 1) * kstep;
;             const char* a2 = last ? nA : cA + (size_t)(t + 2) * kstep; const char* b2 = last ? nB : cB + (size_t)(t + 2) * kstep;
;             const char* a3 = a2 + kstep; const char* b3 = b2 + kstep;
;             if (last && has_next) S.a_ready(nxt);
;             PG8_LDB(B0, 0, 0); PG8_SCHED; PG8_LDA(At, 0, 0); PG8_STAGE(PG8_SA(1, 1), a1 + hstep, voffA);
;             PG8_WAIT_L(8); PG8_BAR; PG8_WAIT_L(0); PG8_MMA(0, 0, At, B0); PG8_BAR; PG8_SCHED;
;             PG8_LDB(B1, 0, 1); PG8_STAGE(PG8_SB(0, 0), b2, voffB);
;             PG8_BAR; PG8_WAIT_L(0); PG8_MMA(0, 1, At, B1); PG8_BAR;
;             PG8_LDA(At, 0, 1); PG8_STAGE(PG8_SA(0, 0), a2, voffA);
;             PG8_BAR; PG8_WAIT_L(0); PG8_MMA(1, 0, At, B0); PG8_BAR; PG8_SCHED;
;             PG8_STAGE(PG8_SB(0, 1), b2 + hstep, voffB);
;             PG8_WAIT_V(6); PG8_BAR; PG8_MMA(1, 1, At, B1); PG8_BAR;
.LBB0_1129:
	s_add_u32 s16, s14, 0xfffc0080
	s_addc_u32 s17, s15, -1
	s_add_i32 s41, 0, 0x10000
	v_add_u32_e32 v175, s41, v149
	ds_read_b128 v[144:147], v175
	ds_read_b128 v[152:155], v175 offset:1024
	ds_read_b128 v[156:159], v175 offset:2048
	ds_read_b128 v[176:179], v175 offset:3072
	s_cmp_eq_u32 s40, 12
	s_cselect_b32 s19, s9, s17
	s_cselect_b32 s18, s36, s16
	s_cselect_b32 s17, s7, s39
	s_cselect_b32 s16, s37, s38
	v_lshl_add_u64 v[212:213], s[14:15], 0, v[140:141]
	s_add_i32 m0, s25, 0xc000
	ds_read_b128 v[180:183], v151
	ds_read_b128 v[184:187], v151 offset:1024
	ds_read_b128 v[188:191], v151 offset:2048
	ds_read_b128 v[192:195], v151 offset:3072
	ds_read_b128 v[196:199], v151 offset:4096
	ds_read_b128 v[200:203], v151 offset:5120
	ds_read_b128 v[204:207], v151 offset:6144
	ds_read_b128 v[208:211], v151 offset:7168
	global_load_lds_dwordx4 v[212:213], off
	v_lshl_add_u64 v[212:213], s[14:15], 0, v[142:143]
	s_add_i32 m0, s25, 0xe000
	s_nop 0
	global_load_lds_dwordx4 v[212:213], off
	s_waitcnt lgkmcnt(8)
	s_barrier
	s_waitcnt lgkmcnt(0)
	s_setprio 1
	s_waitcnt lgkmcnt(0)
	v_mfma_f32_16x16x32_bf16 v[126:129], v[144:147], v[180:183], v[126:129]
	v_mfma_f32_16x16x32_bf16 v[118:121], v[156:159], v[180:183], v[118:121]
	v_mfma_f32_16x16x32_bf16 v[110:113], v[144:147], v[188:191], v[110:113]
	v_mfma_f32_16x16x32_bf16 v[102:105], v[156:159], v[188:191], v[102:105]
	v_mfma_f32_16x16x32_bf16 v[94:97], v[144:147], v[196:199], v[94:97]
	v_mfma_f32_16x16x32_bf16 v[86:89], v[156:159], v[196:199], v[86:89]
	v_mfma_f32_16x16x32_bf16 v[78:81], v[144:147], v[204:207], v[78:81]
	v_mfma_f32_16x16x32_bf16 v[70:73], v[156:159], v[204:207], v[70:73]
	v_mfma_f32_16x16x32_bf16 v[126:129], v[152:155], v[184:187], v[126:129]
	v_mfma_f32_16x16x32_bf16 v[118:121], v[176:179], v[184:187], v[118:121]
	v_mfma_f32_16x16x32_bf16 v[110:113], v[152:155], v[192:195], v[110:113]
	v_mfma_f32_16x16x32_bf16 v[102:105], v[176:179], v[192:195], v[102:105]
	v_mfma_f32_16x16x32_bf16 v[94:97], v[152:155], v[200:203], v[94:97]
	v_mfma_f32_16x16x32_bf16 v[86:89], v[176:179], v[200:203], v[86:89]
	v_mfma_f32_16x16x32_bf16 v[78:81], v[152:155], v[208:211], v[78:81]
	v_mfma_f32_16x16x32_bf16 v[70:73], v[176:179], v[208:211], v[70:73]
	s_setprio 0
	s_barrier
	s_add_i32 s50, 0, 0x14000
	s_add_i32 s41, s41, s24
	v_add_u32_e32 v175, s50, v149
	v_lshl_add_u64 v[228:229], s[16:17], 0, v[0:1]
	s_mov_b32 m0, s41
	ds_read_b128 v[212:215], v175
	ds_read_b128 v[216:219], v175 offset:1024
	ds_read_b128 v[220:223], v175 offset:2048
	ds_read_b128 v[224:227], v175 offset:3072
	global_load_lds_dwordx4 v[228:229], off
	v_lshl_add_u64 v[230:231], s[16:17], 0, v[134:135]
	s_add_i32 m0, s41, 0x2000
	s_nop 0
	global_load_lds_dwordx4 v[230:231], off
	s_barrier
	s_waitcnt lgkmcnt(0)
	s_setprio 1
	s_waitcnt lgkmcnt(0)
	v_mfma_f32_16x16x32_bf16 v[122:125], v[212:215], v[180:183], v[122:125]
	v_mfma_f32_16x16x32_bf16 v[114:117], v[220:223], v[180:183], v[114:117]
	v_mfma_f32_16x16x32_bf16 v[106:109], v[212:215], v[188:191], v[106:109]
	v_mfma_f32_16x16x32_bf16 v[98:101], v[220:223], v[188:191], v[98:101]
	v_mfma_f32_16x16x32_bf16 v[90:93], v[212:215], v[196:199], v[90:93]
	v_mfma_f32_16x16x32_bf16 v[82:85], v[220:223], v[196:199], v[82:85]
	v_mfma_f32_16x16x32_bf16 v[74:77], v[212:215], v[204:207], v[74:77]
	v_mfma_f32_16x16x32_bf16 v[66:69], v[220:223], v[204:207], v[66:69]
	v_mfma_f32_16x16x32_bf16 v[122:125], v[216:219], v[184:187], v[122:125]
	v_mfma_f32_16x16x32_bf16 v[114:117], v[224:227], v[184:187], v[114:117]
	v_mfma_f32_16x16x32_bf16 v[106:109], v[216:219], v[192:195], v[106:109]
	v_mfma_f32_16x16x32_bf16 v[98:101], v[224:227], v[192:195], v[98:101]
	v_mfma_f32_16x16x32_bf16 v[90:93], v[216:219], v[200:203], v[90:93]
	v_mfma_f32_16x16x32_bf16 v[82:85], v[224:227], v[200:203], v[82:85]
	v_mfma_f32_16x16x32_bf16 v[74:77], v[216:219], v[208:211], v[74:77]
	v_mfma_f32_16x16x32_bf16 v[66:69], v[224:227], v[208:211], v[66:69]
	s_setprio 0
	s_mov_b32 m0, s25
	v_lshl_add_u64 v[232:233], s[18:19], 0, v[138:139]
	s_barrier
	ds_read_b128 v[180:183], v151 offset:16384
	ds_read_b128 v[184:187], v151 offset:17408
	ds_read_b128 v[188:191], v151 offset:18432
	ds_read_b128 v[192:195], v151 offset:19456
	ds_read_b128 v[196:199], v151 offset:20480
	ds_read_b128 v[200:203], v151 offset:21504
	ds_read_b128 v[204:207], v151 offset:22528
	ds_read_b128 v[208:211], v151 offset:23552
	global_load_lds_dwordx4 v[232:233], off
	v_lshl_add_u64 v[234:235], s[18:19], 0, v[136:137]
	s_mov_b32 m0, s26
	s_nop 0
	global_load_lds_dwordx4 v[234:235], off
	s_barrier
	s_waitcnt lgkmcnt(0)
	s_setprio 1
	s_waitcnt lgkmcnt(0)
	v_mfma_f32_16x16x32_bf16 v[62:65], v[144:147], v[180:183], v[62:65]
	v_mfma_f32_16x16x32_bf16 v[54:57], v[156:159], v[180:183], v[54:57]
	v_mfma_f32_16x16x32_bf16 v[46:49], v[144:147], v[188:191], v[46:49]
	v_mfma_f32_16x16x32_bf16 v[38:41], v[156:159], v[188:191], v[38:41]
	v_mfma_f32_16x16x32_bf16 v[30:33], v[144:147], v[196:199], v[30:33]
	v_mfma_f32_16x16x32_bf16 v[22:25], v[156:159], v[196:199], v[22:25]
	v_mfma_f32_16x16x32_bf16 v[14:17], v[144:147], v[204:207], v[14:17]
	v_mfma_f32_16x16x32_bf16 v[6:9], v[156:159], v[204:207], v[6:9]
	v_mfma_f32_16x16x32_bf16 v[62:65], v[152:155], v[184:187], v[62:65]
	v_mfma_f32_16x16x32_bf16 v[54:57], v[176:179], v[184:187], v[54:57]
	v_mfma_f32_16x16x32_bf16 v[46:49], v[152:155], v[192:195], v[46:49]
	v_mfma_f32_16x16x32_bf16 v[38:41], v[176:179], v[192:195], v[38:41]
	v_mfma_f32_16x16x32_bf16 v[30:33], v[152:155], v[200:203], v[30:33]
	v_mfma_f32_16x16x32_bf16 v[22:25], v[176:179], v[200:203], v[22:25]
	v_mfma_f32_16x16x32_bf16 v[14:17], v[152:155], v[208:211], v[14:17]
	v_mfma_f32_16x16x32_bf16 v[6:9], v[176:179], v[208:211], v[6:9]
	s_setprio 0
	s_barrier
; #define PG8_STAGE(bufoff, gbase, voff) do { _Pragma("unroll") for (int _i = 0; _i < 2; ++_i) \
;         __builtin_amdgcn_global_load_lds((const unsigned*)((const char*)(gbase) + (voff)[_i]), (PG8_LAS unsigned*)(lds + (bufoff) + ldsw + _i * 8192), 16, 0, 0); } while (0)
; #define PG8_LDA(dst, b, h) do { _Pragma("unroll") for (int m = 0; m < 4; ++m) _Pragma("unroll") for (int k = 0; k < 2; ++k) dst[m][k] = *(const PG8_LAS bf16x8*)(lds + PG8_SA(b, h) + aoff + m * 2048 + k * 1024); } while (0)
; #define PG8_LDB(dst, b, h) do { _Pragma("unroll") for (int n = 0; n < 2; ++n) _Pragma("unroll") for (int k = 0; k < 2; ++k) dst[n][k] = *(const PG8_LAS bf16x8*)(lds + PG8_SB(b, h) + boff + n * 2048 + k * 1024); } while (0)
; #define PG8_MMA(ai, bj, At, Bt) do { __builtin_amdgcn_s_setprio(1); _Pragma("unroll") for (int m = 0; m < 4; ++m) _Pragma("unroll") for (int n = 0; n < 2; ++n) _Pragma("unroll") for (int k = 0; k < 2; ++k) \
;         acc[ai][bj][m][n] = __builtin_amdgcn_mfma_f32_16x16x32_bf16(Bt[n][k], At[m][k], acc[ai][bj][m][n], 0, 0, 0); __builtin_amdgcn_s_setprio(0); } while (0)
; #define PG8_WAIT_V(n) asm volatile("s_waitcnt vmcnt(" #n ")" ::: "memory")
; #define PG8_WAIT_L(n) asm volatile("s_waitcnt lgkmcnt(" #n ")" ::: "memory")
; #define PG8_BAR __builtin_amdgcn_s_barrier()
; #define PG8_SCHED __builtin_amdgcn_sched_barrier(0)
; template <class Epi, class Sched>
; __device__ __forceinline__ void gemm_phase(PG8_LAS unsigned char* lds, const Gemm g, const Sched& S, const Epi& E) {
;     ...
;             PG8_STAGE(PG8_SB(0, 1), b2 + hstep, voffB);
;             PG8_WAIT_V(6); PG8_BAR; PG8_MMA(1, 1, At, B1); PG8_BAR;
;             PG8_LDB(B0, 1, 0); PG8_SCHED; PG8_LDA(At, 1, 0); PG8_STAGE(PG8_SA(0, 1), a2 + hstep, voffA);
;             PG8_WAIT_L(8); PG8_BAR; PG8_WAIT_L(0); PG8_MMA(0, 0, At, B0); PG8_BAR; PG8_SCHED;
;             PG8_LDB(B1, 1, 1); PG8_STAGE(PG8_SB(1, 0), b3, voffB);
;             PG8_BAR; PG8_WAIT_L(0); PG8_MMA(0, 1, At, B1); PG8_BAR;
;             PG8_LDA(At, 1, 1); PG8_STAGE(PG8_SA(1, 0), a3, voffA);
;             PG8_BAR; PG8_WAIT_L(0); PG8_MMA(1, 0, At, B0); PG8_BAR; PG8_SCHED;
	s_add_u32 s44, s16, 0x40000
	s_addc_u32 s45, s17, 0
	s_add_i32 s41, s50, s24
	v_lshl_add_u64 v[144:145], s[44:45], 0, v[0:1]
	s_mov_b32 m0, s41
	s_nop 0
	global_load_lds_dwordx4 v[144:145], off
	v_lshl_add_u64 v[144:145], s[44:45], 0, v[134:135]
	s_add_i32 m0, s41, 0x2000
	s_nop 0
	global_load_lds_dwordx4 v[144:145], off
	s_waitcnt vmcnt(6)
	s_barrier
	s_setprio 1
	v_mfma_f32_16x16x32_bf16 v[58:61], v[212:215], v[180:183], v[58:61]
	v_mfma_f32_16x16x32_bf16 v[50:53], v[220:223], v[180:183], v[50:53]
	v_mfma_f32_16x16x32_bf16 v[42:45], v[212:215], v[188:191], v[42:45]
	v_mfma_f32_16x16x32_bf16 v[34:37], v[220:223], v[188:191], v[34:37]
	v_mfma_f32_16x16x32_bf16 v[26:29], v[212:215], v[196:199], v[26:29]
	v_mfma_f32_16x16x32_bf16 v[18:21], v[220:223], v[196:199], v[18:21]
	v_mfma_f32_16x16x32_bf16 v[10:13], v[212:215], v[204:207], v[10:13]
	v_mfma_f32_16x16x32_bf16 v[2:5], v[220:223], v[204:207], v[2:5]
	v_mfma_f32_16x16x32_bf16 v[58:61], v[216:219], v[184:187], v[58:61]
	v_mfma_f32_16x16x32_bf16 v[50:53], v[224:227], v[184:187], v[50:53]
	v_mfma_f32_16x16x32_bf16 v[42:45], v[216:219], v[192:195], v[42:45]
	v_mfma_f32_16x16x32_bf16 v[34:37], v[224:227], v[192:195], v[34:37]
	v_mfma_f32_16x16x32_bf16 v[26:29], v[216:219], v[200:203], v[26:29]
	v_mfma_f32_16x16x32_bf16 v[18:21], v[224:227], v[200:203], v[18:21]
	v_mfma_f32_16x16x32_bf16 v[10:13], v[216:219], v[208:211], v[10:13]
	v_mfma_f32_16x16x32_bf16 v[2:5], v[224:227], v[208:211], v[2:5]
	s_setprio 0
	s_add_i32 s41, 0, 0x18000
	v_add_u32_e32 v175, s41, v149
	s_barrier
	ds_read_b128 v[144:147], v175
	ds_read_b128 v[152:155], v175 offset:1024
	ds_read_b128 v[156:159], v175 offset:2048
	ds_read_b128 v[176:179], v175 offset:3072
	s_add_u32 s18, s18, 0x40000
	s_addc_u32 s19, s19, 0
	s_mov_b32 m0, s27
	v_lshl_add_u64 v[212:213], s[18:19], 0, v[138:139]
	ds_read_b128 v[180:183], v151 offset:32768
	ds_read_b128 v[184:187], v151 offset:33792
	ds_read_b128 v[188:191], v151 offset:34816
	ds_read_b128 v[192:195], v151 offset:35840
	ds_read_b128 v[196:199], v151 offset:36864
	ds_read_b128 v[200:203], v151 offset:37888
	ds_read_b128 v[204:207], v151 offset:38912
	ds_read_b128 v[208:211], v151 offset:39936
	global_load_lds_dwordx4 v[212:213], off
	v_lshl_add_u64 v[212:213], s[18:19], 0, v[136:137]
	s_mov_b32 m0, s28
	s_nop 0
	global_load_lds_dwordx4 v[212:213], off
	s_waitcnt lgkmcnt(8)
	s_barrier
	s_waitcnt lgkmcnt(0)
	s_setprio 1
	s_waitcnt lgkmcnt(0)
	v_mfma_f32_16x16x32_bf16 v[126:129], v[144:147], v[180:183], v[126:129]
	v_mfma_f32_16x16x32_bf16 v[118:121], v[156:159], v[180:183], v[118:121]
	v_mfma_f32_16x16x32_bf16 v[110:113], v[144:147], v[188:191], v[110:113]
	v_mfma_f32_16x16x32_bf16 v[102:105], v[156:159], v[188:191], v[102:105]
	v_mfma_f32_16x16x32_bf16 v[94:97], v[144:147], v[196:199], v[94:97]
	v_mfma_f32_16x16x32_bf16 v[86:89], v[156:159], v[196:199], v[86:89]
	v_mfma_f32_16x16x32_bf16 v[78:81], v[144:147], v[204:207], v[78:81]
	v_mfma_f32_16x16x32_bf16 v[70:73], v[156:159], v[204:207], v[70:73]
	v_mfma_f32_16x16x32_bf16 v[126:129], v[152:155], v[184:187], v[126:129]
	v_mfma_f32_16x16x32_bf16 v[118:121], v[176:179], v[184:187], v[118:121]
	v_mfma_f32_16x16x32_bf16 v[110:113], v[152:155], v[192:195], v[110:113]
	v_mfma_f32_16x16x32_bf16 v[102:105], v[176:179], v[192:195], v[102:105]
	v_mfma_f32_16x16x32_bf16 v[94:97], v[152:155], v[200:203], v[94:97]
	v_mfma_f32_16x16x32_bf16 v[86:89], v[176:179], v[200:203], v[86:89]
	v_mfma_f32_16x16x32_bf16 v[78:81], v[152:155], v[208:211], v[78:81]
	v_mfma_f32_16x16x32_bf16 v[70:73], v[176:179], v[208:211], v[70:73]
	s_setprio 0
	s_barrier
	s_add_i32 s18, 0, 0x1c000
	s_add_i32 s19, s41, s24
	v_add_u32_e32 v175, s18, v149
	v_lshl_add_u64 v[228:229], v[228:229], 0, s[70:71]
	s_mov_b32 m0, s19
	ds_read_b128 v[212:215], v175
	ds_read_b128 v[216:219], v175 offset:1024
	ds_read_b128 v[220:223], v175 offset:2048
	ds_read_b128 v[224:227], v175 offset:3072
	global_load_lds_dwordx4 v[228:229], off
	v_lshl_add_u64 v[228:229], v[230:231], 0, s[70:71]
	s_add_i32 m0, s19, 0x2000
	s_nop 0
	global_load_lds_dwordx4 v[228:229], off
	s_barrier
	s_waitcnt lgkmcnt(0)
	s_setprio 1
	s_waitcnt lgkmcnt(0)
	v_mfma_f32_16x16x32_bf16 v[122:125], v[212:215], v[180:183], v[122:125]
	v_mfma_f32_16x16x32_bf16 v[114:117], v[220:223], v[180:183], v[114:117]
	v_mfma_f32_16x16x32_bf16 v[106:109], v[212:215], v[188:191], v[106:109]
	v_mfma_f32_16x16x32_bf16 v[98:101], v[220:223], v[188:191], v[98:101]
	v_mfma_f32_16x16x32_bf16 v[90:93], v[212:215], v[196:199], v[90:93]
	v_mfma_f32_16x16x32_bf16 v[82:85], v[220:223], v[196:199], v[82:85]
	v_mfma_f32_16x16x32_bf16 v[74:77], v[212:215], v[204:207], v[74:77]
	v_mfma_f32_16x16x32_bf16 v[66:69], v[220:223], v[204:207], v[66:69]
	v_mfma_f32_16x16x32_bf16 v[122:125], v[216:219], v[184:187], v[122:125]
	v_mfma_f32_16x16x32_bf16 v[114:117], v[224:227], v[184:187], v[114:117]
	v_mfma_f32_16x16x32_bf16 v[106:109], v[216:219], v[192:195], v[106:109]
	v_mfma_f32_16x16x32_bf16 v[98:101], v[224:227], v[192:195], v[98:101]
	v_mfma_f32_16x16x32_bf16 v[90:93], v[216:219], v[200:203], v[90:93]
	v_mfma_f32_16x16x32_bf16 v[82:85], v[224:227], v[200:203], v[82:85]
	v_mfma_f32_16x16x32_bf16 v[74:77], v[216:219], v[208:211], v[74:77]
	v_mfma_f32_16x16x32_bf16 v[66:69], v[224:227], v[208:211], v[66:69]
	s_setprio 0
	s_mov_b32 m0, s29
	v_lshl_add_u64 v[228:229], v[232:233], 0, s[70:71]
	s_barrier
	ds_read_b128 v[180:183], v151 offset:49152
	ds_read_b128 v[184:187], v151 offset:50176
	ds_read_b128 v[188:191], v151 offset:51200
	ds_read_b128 v[192:195], v151 offset:52224
	ds_read_b128 v[196:199], v151 offset:53248
	ds_read_b128 v[200:203], v151 offset:54272
	ds_read_b128 v[204:207], v151 offset:55296
	ds_read_b128 v[208:211], v151 offset:56320
	global_load_lds_dwordx4 v[228:229], off
	v_lshl_add_u64 v[228:229], v[234:235], 0, s[70:71]
	s_mov_b32 m0, s30
	s_nop 0
	global_load_lds_dwordx4 v[228:229], off
	s_barrier
; #define PG8_STAGE(bufoff, gbase, voff) do { _Pragma("unroll") for (int _i = 0; _i < 2; ++_i) \
;         __builtin_amdgcn_global_load_lds((const unsigned*)((const char*)(gbase) + (voff)[_i]), (PG8_LAS unsigned*)(lds + (bufoff) + ldsw + _i * 8192), 16, 0, 0); } while (0)
; #define PG8_MMA(ai, bj, At, Bt) do { __builtin_amdgcn_s_setprio(1); _Pragma("unroll") for (int m = 0; m < 4; ++m) _Pragma("unroll") for (int n = 0; n < 2; ++n) _Pragma("unroll") for (int k = 0; k < 2; ++k) \
;         acc[ai][bj][m][n] = __builtin_amdgcn_mfma_f32_16x16x32_bf16(Bt[n][k], At[m][k], acc[ai][bj][m][n], 0, 0, 0); __builtin_amdgcn_s_setprio(0); } while (0)
; #define PG8_WAIT_V(n) asm volatile("s_waitcnt vmcnt(" #n ")" ::: "memory")
; #define PG8_WAIT_L(n) asm volatile("s_waitcnt lgkmcnt(" #n ")" ::: "memory")
; #define PG8_BAR __builtin_amdgcn_s_barrier()
; #define PG8_SCHED __builtin_amdgcn_sched_barrier(0)
; __device__ __forceinline__ unsigned pk2(float lo, float hi) { return pg8::cvt_pk_bf16(lo, hi); }
; template <class Epi, class Sched>
; __device__ __forceinline__ void gemm_phase(PG8_LAS unsigned char* lds, const Gemm g, const Sched& S, const Epi& E) {
;     ...
;             PG8_BAR; PG8_WAIT_L(0); PG8_MMA(1, 0, At, B0); PG8_BAR; PG8_SCHED;
;             PG8_STAGE(PG8_SB(1, 1), b3 + hstep, voffB);
;             PG8_WAIT_V(6); PG8_BAR; PG8_MMA(1, 1, At, B1); PG8_BAR;
;         }
;         if constexpr (!Epi::AFTER_DRAIN) { E(acc, cur, wr, wc, fr, fq); S.done(cur); }
;     __device__ __forceinline__ void operator()(const f32x4 (&acc)[2][2][4][2], const pg8::Unit& u, int wr, int wc, int fr, int fq) const {
;         const int row0 = u.pm * 256 + wr * 64 + fr, col0 = u.pn * 128 + wc * 32 + 8 * fq;
; #pragma unroll
;         for (int ai = 0; ai < 2; ++ai)
; #pragma unroll
;             for (int m = 0; m < 4; ++m) {
;                 bf16_t* p = O + (size_t)(row0 + ai * 128 + m * 16) * FF + col0;
;                 const f32x4 g0 = acc[ai][0][m][0], g1 = acc[ai][0][m][1], u0 = acc[ai][1][m][0], u1 = acc[ai][1][m][1];
;                 u32x4 w;
;                 w.x = pk2(silu(g0[0]) * u0[0], silu(g0[1]) * u0[1]); w.y = pk2(silu(g0[2]) * u0[2], silu(g0[3]) * u0[3]);
;                 w.z = pk2(silu(g1[0]) * u1[0], silu(g1[1]) * u1[1]); w.w = pk2(silu(g1[2]) * u1[2], silu(g1[3]) * u1[3]);
;                 *(u32x4*)p = w;
;             }
;     }
	s_waitcnt lgkmcnt(0)
	s_setprio 1
	s_waitcnt lgkmcnt(0)
	v_mfma_f32_16x16x32_bf16 v[62:65], v[144:147], v[180:183], v[62:65]
	v_mfma_f32_16x16x32_bf16 v[54:57], v[156:159], v[180:183], v[54:57]
	v_mfma_f32_16x16x32_bf16 v[46:49], v[144:147], v[188:191], v[46:49]
	v_mfma_f32_16x16x32_bf16 v[38:41], v[156:159], v[188:191], v[38:41]
	v_mfma_f32_16x16x32_bf16 v[30:33], v[144:147], v[196:199], v[30:33]
	v_mfma_f32_16x16x32_bf16 v[22:25], v[156:159], v[196:199], v[22:25]
	v_mfma_f32_16x16x32_bf16 v[14:17], v[144:147], v[204:207], v[14:17]
	v_mfma_f32_16x16x32_bf16 v[6:9], v[156:159], v[204:207], v[6:9]
	v_mfma_f32_16x16x32_bf16 v[62:65], v[152:155], v[184:187], v[62:65]
	v_mfma_f32_16x16x32_bf16 v[54:57], v[176:179], v[184:187], v[54:57]
	v_mfma_f32_16x16x32_bf16 v[46:49], v[152:155], v[192:195], v[46:49]
	v_mfma_f32_16x16x32_bf16 v[38:41], v[176:179], v[192:195], v[38:41]
	v_mfma_f32_16x16x32_bf16 v[30:33], v[152:155], v[200:203], v[30:33]
	v_mfma_f32_16x16x32_bf16 v[22:25], v[176:179], v[200:203], v[22:25]
	v_mfma_f32_16x16x32_bf16 v[14:17], v[152:155], v[208:211], v[14:17]
	v_mfma_f32_16x16x32_bf16 v[6:9], v[176:179], v[208:211], v[6:9]
	s_setprio 0
	s_barrier
	s_add_u32 s16, s16, 0x40080
	s_addc_u32 s17, s17, 0
	s_add_i32 s18, s18, s24
	v_lshl_add_u64 v[144:145], s[16:17], 0, v[0:1]
	s_mov_b32 m0, s18
	s_nop 0
	global_load_lds_dwordx4 v[144:145], off
	v_lshl_add_u64 v[144:145], s[16:17], 0, v[134:135]
	s_add_i32 m0, s18, 0x2000
	s_nop 0
	global_load_lds_dwordx4 v[144:145], off
	s_waitcnt vmcnt(6)
	s_barrier
	s_setprio 1
	v_mfma_f32_16x16x32_bf16 v[58:61], v[212:215], v[180:183], v[58:61]
	v_mfma_f32_16x16x32_bf16 v[50:53], v[220:223], v[180:183], v[50:53]
	v_mfma_f32_16x16x32_bf16 v[42:45], v[212:215], v[188:191], v[42:45]
	v_mfma_f32_16x16x32_bf16 v[34:37], v[220:223], v[188:191], v[34:37]
	v_mfma_f32_16x16x32_bf16 v[26:29], v[212:215], v[196:199], v[26:29]
	v_mfma_f32_16x16x32_bf16 v[18:21], v[220:223], v[196:199], v[18:21]
	v_mfma_f32_16x16x32_bf16 v[10:13], v[212:215], v[204:207], v[10:13]
	v_mfma_f32_16x16x32_bf16 v[2:5], v[220:223], v[204:207], v[2:5]
	v_mfma_f32_16x16x32_bf16 v[58:61], v[216:219], v[184:187], v[58:61]
	v_mfma_f32_16x16x32_bf16 v[50:53], v[224:227], v[184:187], v[50:53]
	v_mfma_f32_16x16x32_bf16 v[42:45], v[216:219], v[192:195], v[42:45]
	v_mfma_f32_16x16x32_bf16 v[34:37], v[224:227], v[192:195], v[34:37]
	v_mfma_f32_16x16x32_bf16 v[26:29], v[216:219], v[200:203], v[26:29]
	v_mfma_f32_16x16x32_bf16 v[18:21], v[224:227], v[200:203], v[18:21]
	v_mfma_f32_16x16x32_bf16 v[10:13], v[216:219], v[208:211], v[10:13]
	v_mfma_f32_16x16x32_bf16 v[2:5], v[224:227], v[208:211], v[2:5]
	s_setprio 0
	s_add_i32 s40, s40, 2
	s_add_u32 s14, s14, 0x100
	s_addc_u32 s15, s15, 0
	s_add_u32 s38, s38, 0x100
	s_addc_u32 s39, s39, 0
	s_cmp_gt_u32 s40, 13
	s_barrier
	s_cbranch_scc0 .LBB0_1129
	v_mul_f32_e32 v153, 0xbfb8aa3b, v126
	v_exp_f32_e32 v153, v153
	v_lshl_or_b32 v146, s34, 7, v150
	v_lshl_add_u32 v152, s35, 8, v148
	v_ashrrev_i32_e32 v147, 31, v146
	v_add_f32_e32 v153, 1.0, v153
	v_rcp_f32_e32 v153, v153
	v_mov_b64_e32 v[144:145], s[0:1]
	v_mad_i64_i32 v[154:155], s[14:15], v152, s52, v[144:145]
	v_mul_f32_e32 v126, v126, v153
	v_mul_f32_e32 v122, v126, v122
	v_mul_f32_e32 v126, 0xbfb8aa3b, v127
	v_exp_f32_e32 v126, v126
	v_lshlrev_b64 v[146:147], 1, v[146:147]
	v_lshl_add_u64 v[154:155], v[154:155], 0, v[146:147]
	s_and_b64 vcc, exec, s[4:5]
	v_add_f32_e32 v126, 1.0, v126
	v_rcp_f32_e32 v126, v126
	s_mov_b32 s34, s6
	s_mov_b32 s35, s8
	s_mov_b64 s[16:17], s[12:13]
	v_mul_f32_e32 v126, v127, v126
	v_mul_f32_e32 v123, v126, v123
	v_cvt_pk_bf16_f32 v122, v122, v123
	v_mul_f32_e32 v123, 0xbfb8aa3b, v128
	v_exp_f32_e32 v123, v123
	s_nop 0
	v_add_f32_e32 v123, 1.0, v123
	v_rcp_f32_e32 v123, v123
	s_nop 0
	v_mul_f32_e32 v123, v128, v123
	v_mul_f32_e32 v123, v123, v124
	v_mul_f32_e32 v124, 0xbfb8aa3b, v129
	v_exp_f32_e32 v124, v124
	s_nop 0
	v_add_f32_e32 v124, 1.0, v124
	v_rcp_f32_e32 v124, v124
	s_nop 0
	v_mul_f32_e32 v124, v129, v124
	v_mul_f32_e32 v124, v124, v125
	v_cvt_pk_bf16_f32 v123, v123, v124
	v_mul_f32_e32 v124, 0xbfb8aa3b, v118
	v_exp_f32_e32 v124, v124
	s_nop 0
	v_add_f32_e32 v124, 1.0, v124
	v_rcp_f32_e32 v124, v124
	s_nop 0
	v_mul_f32_e32 v118, v118, v124
	v_mul_f32_e32 v114, v118, v114
	v_mul_f32_e32 v118, 0xbfb8aa3b, v119
	v_exp_f32_e32 v118, v118
	s_nop 0
	v_add_f32_e32 v118, 1.0, v118
	v_rcp_f32_e32 v118, v118
	s_nop 0
	v_mul_f32_e32 v118, v119, v118
	v_mul_f32_e32 v115, v118, v115
	v_cvt_pk_bf16_f32 v124, v114, v115
	v_mul_f32_e32 v114, 0xbfb8aa3b, v120
	v_exp_f32_e32 v114, v114
	v_mul_f32_e32 v115, 0xbfb8aa3b, v121
	v_exp_f32_e32 v115, v115
	v_add_f32_e32 v114, 1.0, v114
	v_rcp_f32_e32 v114, v114
	v_add_f32_e32 v115, 1.0, v115
	v_rcp_f32_e32 v115, v115
	v_mul_f32_e32 v114, v120, v114
	v_mul_f32_e32 v114, v114, v116
	v_mul_f32_e32 v116, 0xbfb8aa3b, v110
	v_exp_f32_e32 v116, v116
	v_mul_f32_e32 v115, v121, v115
	v_mul_f32_e32 v115, v115, v117
	v_cvt_pk_bf16_f32 v125, v114, v115
	v_add_f32_e32 v116, 1.0, v116
	v_rcp_f32_e32 v116, v116
	global_store_dwordx4 v[154:155], v[122:125], off sc1
	v_or_b32_e32 v114, 16, v152
	v_mad_i64_i32 v[114:115], s[14:15], v114, s52, v[144:145]
	v_mul_f32_e32 v110, v110, v116
	v_mul_f32_e32 v106, v110, v106
	v_mul_f32_e32 v110, 0xbfb8aa3b, v111
	v_exp_f32_e32 v110, v110
	v_lshl_add_u64 v[114:115], v[114:115], 0, v[146:147]
	v_add_f32_e32 v110, 1.0, v110
	v_rcp_f32_e32 v110, v110
	s_nop 0
	v_mul_f32_e32 v110, v111, v110
	v_mul_f32_e32 v107, v110, v107
	v_cvt_pk_bf16_f32 v106, v106, v107
	v_mul_f32_e32 v107, 0xbfb8aa3b, v112
	v_exp_f32_e32 v107, v107
	s_nop 0
	v_add_f32_e32 v107, 1.0, v107
; __device__ __forceinline__ unsigned pk2(float lo, float hi) { return pg8::cvt_pk_bf16(lo, hi); }
; __device__ __forceinline__ float silu(float x) { return x * __builtin_amdgcn_rcpf(1.0f + __expf(-x)); }
;     __device__ __forceinline__ void operator()(const f32x4 (&acc)[2][2][4][2], const pg8::Unit& u, int wr, int wc, int fr, int fq) const {
;         const int row0 = u.pm * 256 + wr * 64 + fr, col0 = u.pn * 128 + wc * 32 + 8 * fq;
; #pragma unroll
;         for (int ai = 0; ai < 2; ++ai)
; #pragma unroll
;             for (int m = 0; m < 4; ++m) {
;                 bf16_t* p = O + (size_t)(row0 + ai * 128 + m * 16) * FF + col0;
;                 const f32x4 g0 = acc[ai][0][m][0], g1 = acc[ai][0][m][1], u0 = acc[ai][1][m][0], u1 = acc[ai][1][m][1];
;                 u32x4 w;
;                 w.x = pk2(silu(g0[0]) * u0[0], silu(g0[1]) * u0[1]); w.y = pk2(silu(g0[2]) * u0[2], silu(g0[3]) * u0[3]);
;                 w.z = pk2(silu(g1[0]) * u1[0], silu(g1[1]) * u1[1]); w.w = pk2(silu(g1[2]) * u1[2], silu(g1[3]) * u1[3]);
;                 *(u32x4*)p = w;
;             }
;     }
	v_rcp_f32_e32 v107, v107
	s_nop 0
	v_mul_f32_e32 v107, v112, v107
	v_mul_f32_e32 v107, v107, v108
	v_mul_f32_e32 v108, 0xbfb8aa3b, v113
	v_exp_f32_e32 v108, v108
	s_nop 0
	v_add_f32_e32 v108, 1.0, v108
	v_rcp_f32_e32 v108, v108
	s_nop 0
	v_mul_f32_e32 v108, v113, v108
	v_mul_f32_e32 v108, v108, v109
	v_cvt_pk_bf16_f32 v107, v107, v108
	v_mul_f32_e32 v108, 0xbfb8aa3b, v102
	v_exp_f32_e32 v108, v108
	s_nop 0
	v_add_f32_e32 v108, 1.0, v108
	v_rcp_f32_e32 v108, v108
	s_nop 0
	v_mul_f32_e32 v102, v102, v108
	v_mul_f32_e32 v98, v102, v98
	v_mul_f32_e32 v102, 0xbfb8aa3b, v103
	v_exp_f32_e32 v102, v102
	s_nop 0
	v_add_f32_e32 v102, 1.0, v102
	v_rcp_f32_e32 v102, v102
	s_nop 0
	v_mul_f32_e32 v102, v103, v102
	v_mul_f32_e32 v99, v102, v99
	v_cvt_pk_bf16_f32 v108, v98, v99
	v_mul_f32_e32 v98, 0xbfb8aa3b, v104
	v_exp_f32_e32 v98, v98
	v_mul_f32_e32 v99, 0xbfb8aa3b, v105
	v_exp_f32_e32 v99, v99
	v_add_f32_e32 v98, 1.0, v98
	v_rcp_f32_e32 v98, v98
	v_add_f32_e32 v99, 1.0, v99
	v_rcp_f32_e32 v99, v99
	v_mul_f32_e32 v98, v104, v98
	v_mul_f32_e32 v98, v98, v100
	v_mul_f32_e32 v100, 0xbfb8aa3b, v94
	v_exp_f32_e32 v100, v100
	v_mul_f32_e32 v99, v105, v99
	v_mul_f32_e32 v99, v99, v101
	v_cvt_pk_bf16_f32 v109, v98, v99
	v_add_f32_e32 v100, 1.0, v100
	v_rcp_f32_e32 v100, v100
	global_store_dwordx4 v[114:115], v[106:109], off sc1
	v_or_b32_e32 v98, 32, v152
	v_mad_i64_i32 v[98:99], s[14:15], v98, s52, v[144:145]
	v_mul_f32_e32 v94, v94, v100
	v_mul_f32_e32 v90, v94, v90
	v_mul_f32_e32 v94, 0xbfb8aa3b, v95
	v_exp_f32_e32 v94, v94
	v_lshl_add_u64 v[98:99], v[98:99], 0, v[146:147]
	v_add_f32_e32 v94, 1.0, v94
	v_rcp_f32_e32 v94, v94
	s_nop 0
	v_mul_f32_e32 v94, v95, v94
	v_mul_f32_e32 v91, v94, v91
	v_cvt_pk_bf16_f32 v90, v90, v91
	v_mul_f32_e32 v91, 0xbfb8aa3b, v96
	v_exp_f32_e32 v91, v91
	s_nop 0
	v_add_f32_e32 v91, 1.0, v91
	v_rcp_f32_e32 v91, v91
	s_nop 0
	v_mul_f32_e32 v91, v96, v91
	v_mul_f32_e32 v91, v91, v92
	v_mul_f32_e32 v92, 0xbfb8aa3b, v97
	v_exp_f32_e32 v92, v92
	s_nop 0
	v_add_f32_e32 v92, 1.0, v92
	v_rcp_f32_e32 v92, v92
	s_nop 0
	v_mul_f32_e32 v92, v97, v92
	v_mul_f32_e32 v92, v92, v93
	v_cvt_pk_bf16_f32 v91, v91, v92
	v_mul_f32_e32 v92, 0xbfb8aa3b, v86
	v_exp_f32_e32 v92, v92
	s_nop 0
	v_add_f32_e32 v92, 1.0, v92
	v_rcp_f32_e32 v92, v92
	s_nop 0
	v_mul_f32_e32 v86, v86, v92
	v_mul_f32_e32 v82, v86, v82
	v_mul_f32_e32 v86, 0xbfb8aa3b, v87
	v_exp_f32_e32 v86, v86
	s_nop 0
	v_add_f32_e32 v86, 1.0, v86
	v_rcp_f32_e32 v86, v86
	s_nop 0
	v_mul_f32_e32 v86, v87, v86
	v_mul_f32_e32 v83, v86, v83
	v_cvt_pk_bf16_f32 v92, v82, v83
	v_mul_f32_e32 v82, 0xbfb8aa3b, v88
	v_exp_f32_e32 v82, v82
	v_mul_f32_e32 v83, 0xbfb8aa3b, v89
	v_exp_f32_e32 v83, v83
	v_add_f32_e32 v82, 1.0, v82
	v_rcp_f32_e32 v82, v82
	v_add_f32_e32 v83, 1.0, v83
	v_rcp_f32_e32 v83, v83
	v_mul_f32_e32 v82, v88, v82
	v_mul_f32_e32 v82, v82, v84
	v_mul_f32_e32 v84, 0xbfb8aa3b, v78
	v_exp_f32_e32 v84, v84
	v_mul_f32_e32 v83, v89, v83
	v_mul_f32_e32 v83, v83, v85
	v_cvt_pk_bf16_f32 v93, v82, v83
	v_add_f32_e32 v84, 1.0, v84
	v_rcp_f32_e32 v84, v84
	global_store_dwordx4 v[98:99], v[90:93], off sc1
	v_or_b32_e32 v82, 48, v152
	v_mad_i64_i32 v[82:83], s[14:15], v82, s52, v[144:145]
	v_mul_f32_e32 v78, v78, v84
	v_mul_f32_e32 v74, v78, v74
	v_mul_f32_e32 v78, 0xbfb8aa3b, v79
	v_exp_f32_e32 v78, v78
	v_lshl_add_u64 v[82:83], v[82:83], 0, v[146:147]
	v_add_f32_e32 v78, 1.0, v78
	v_rcp_f32_e32 v78, v78
	s_nop 0
	v_mul_f32_e32 v78, v79, v78
	v_mul_f32_e32 v75, v78, v75
	v_cvt_pk_bf16_f32 v74, v74, v75
	v_mul_f32_e32 v75, 0xbfb8aa3b, v80
	v_exp_f32_e32 v75, v75
	s_nop 0
	v_add_f32_e32 v75, 1.0, v75
	v_rcp_f32_e32 v75, v75
	s_nop 0
	v_mul_f32_e32 v75, v80, v75
	v_mul_f32_e32 v75, v75, v76
	v_mul_f32_e32 v76, 0xbfb8aa3b, v81
	v_exp_f32_e32 v76, v76
	s_nop 0
	v_add_f32_e32 v76, 1.0, v76
	v_rcp_f32_e32 v76, v76
	s_nop 0
	v_mul_f32_e32 v76, v81, v76
	v_mul_f32_e32 v76, v76, v77
	v_cvt_pk_bf16_f32 v75, v75, v76
	v_mul_f32_e32 v76, 0xbfb8aa3b, v70
	v_exp_f32_e32 v76, v76
	s_nop 0
	v_add_f32_e32 v76, 1.0, v76
	v_rcp_f32_e32 v76, v76
	s_nop 0
	v_mul_f32_e32 v70, v70, v76
	v_mul_f32_e32 v66, v70, v66
	v_mul_f32_e32 v70, 0xbfb8aa3b, v71
	v_exp_f32_e32 v70, v70
	s_nop 0
	v_add_f32_e32 v70, 1.0, v70
	v_rcp_f32_e32 v70, v70
	s_nop 0
	v_mul_f32_e32 v70, v71, v70
	v_mul_f32_e32 v67, v70, v67
	v_cvt_pk_bf16_f32 v76, v66, v67
	v_mul_f32_e32 v66, 0xbfb8aa3b, v72
	v_exp_f32_e32 v66, v66
	v_mul_f32_e32 v67, 0xbfb8aa3b, v73
	v_exp_f32_e32 v67, v67
	v_add_f32_e32 v66, 1.0, v66
	v_rcp_f32_e32 v66, v66
	v_add_f32_e32 v67, 1.0, v67
	v_rcp_f32_e32 v67, v67
	v_mul_f32_e32 v66, v72, v66
	v_mul_f32_e32 v66, v66, v68
	v_mul_f32_e32 v68, 0xbfb8aa3b, v62
	v_exp_f32_e32 v68, v68
	v_mul_f32_e32 v67, v73, v67
	v_mul_f32_e32 v67, v67, v69
	v_cvt_pk_bf16_f32 v77, v66, v67
	v_add_f32_e32 v68, 1.0, v68
	v_rcp_f32_e32 v68, v68
	global_store_dwordx4 v[82:83], v[74:77], off sc1
	v_add_u32_e32 v66, 0x80, v152
	v_mad_i64_i32 v[66:67], s[14:15], v66, s52, v[144:145]
	v_mul_f32_e32 v62, v62, v68
	v_mul_f32_e32 v58, v62, v58
	v_mul_f32_e32 v62, 0xbfb8aa3b, v63
	v_exp_f32_e32 v62, v62
	v_lshl_add_u64 v[66:67], v[66:67], 0, v[146:147]
	v_add_f32_e32 v62, 1.0, v62
	v_rcp_f32_e32 v62, v62
	s_nop 0
	v_mul_f32_e32 v62, v63, v62
	v_mul_f32_e32 v59, v62, v59
	v_cvt_pk_bf16_f32 v58, v58, v59
	v_mul_f32_e32 v59, 0xbfb8aa3b, v64
	v_exp_f32_e32 v59, v59
	s_nop 0
	v_add_f32_e32 v59, 1.0, v59
	v_rcp_f32_e32 v59, v59
	s_nop 0
	v_mul_f32_e32 v59, v64, v59
	v_mul_f32_e32 v59, v59, v60
	v_mul_f32_e32 v60, 0xbfb8aa3b, v65
	v_exp_f32_e32 v60, v60
	s_nop 0
	v_add_f32_e32 v60, 1.0, v60
	v_rcp_f32_e32 v60, v60
	s_nop 0
	v_mul_f32_e32 v60, v65, v60
	v_mul_f32_e32 v60, v60, v61
; #define PG8_WAIT_V(n) asm volatile("s_waitcnt vmcnt(" #n ")" ::: "memory")
; #define PG8_BAR __builtin_amdgcn_s_barrier()
; __device__ __forceinline__ unsigned pk2(float lo, float hi) { return pg8::cvt_pk_bf16(lo, hi); }
; __device__ __forceinline__ float silu(float x) { return x * __builtin_amdgcn_rcpf(1.0f + __expf(-x)); }
; template <class Epi, class Sched>
; __device__ __forceinline__ void gemm_phase(PG8_LAS unsigned char* lds, const Gemm g, const Sched& S, const Epi& E) {
;     ...
;         if (!has_next) break;
; #pragma unroll
;         for (int a = 0; a < 2; ++a)
; #pragma unroll
;             for (int b = 0; b < 2; ++b)
; #pragma unroll
;                 for (int m = 0; m < 4; ++m)
; #pragma unroll
;                     for (int n = 0; n < 2; ++n) acc[a][b][m][n] = (f32x4){0.f, 0.f, 0.f, 0.f};
;         cur = nxt; cA = nA; cB = nB; ++ui;
;     }
;     PG8_WAIT_V(0);
;     if (wr == 0) PG8_BAR;
;     PG8_BAR;
;     __device__ __forceinline__ void operator()(const f32x4 (&acc)[2][2][4][2], const pg8::Unit& u, int wr, int wc, int fr, int fq) const {
;         const int row0 = u.pm * 256 + wr * 64 + fr, col0 = u.pn * 128 + wc * 32 + 8 * fq;
; #pragma unroll
;         for (int ai = 0; ai < 2; ++ai)
; #pragma unroll
;             for (int m = 0; m < 4; ++m) {
;                 bf16_t* p = O + (size_t)(row0 + ai * 128 + m * 16) * FF + col0;
;                 const f32x4 g0 = acc[ai][0][m][0], g1 = acc[ai][0][m][1], u0 = acc[ai][1][m][0], u1 = acc[ai][1][m][1];
;                 u32x4 w;
;                 w.x = pk2(silu(g0[0]) * u0[0], silu(g0[1]) * u0[1]); w.y = pk2(silu(g0[2]) * u0[2], silu(g0[3]) * u0[3]);
;                 w.z = pk2(silu(g1[0]) * u1[0], silu(g1[1]) * u1[1]); w.w = pk2(silu(g1[2]) * u1[2], silu(g1[3]) * u1[3]);
;                 *(u32x4*)p = w;
;             }
;     }
	v_cvt_pk_bf16_f32 v59, v59, v60
	v_mul_f32_e32 v60, 0xbfb8aa3b, v54
	v_exp_f32_e32 v60, v60
	s_nop 0
	v_add_f32_e32 v60, 1.0, v60
	v_rcp_f32_e32 v60, v60
	s_nop 0
	v_mul_f32_e32 v54, v54, v60
	v_mul_f32_e32 v50, v54, v50
	v_mul_f32_e32 v54, 0xbfb8aa3b, v55
	v_exp_f32_e32 v54, v54
	s_nop 0
	v_add_f32_e32 v54, 1.0, v54
	v_rcp_f32_e32 v54, v54
	s_nop 0
	v_mul_f32_e32 v54, v55, v54
	v_mul_f32_e32 v51, v54, v51
	v_cvt_pk_bf16_f32 v60, v50, v51
	v_mul_f32_e32 v50, 0xbfb8aa3b, v56
	v_exp_f32_e32 v50, v50
	v_mul_f32_e32 v51, 0xbfb8aa3b, v57
	v_exp_f32_e32 v51, v51
	v_add_f32_e32 v50, 1.0, v50
	v_rcp_f32_e32 v50, v50
	v_add_f32_e32 v51, 1.0, v51
	v_rcp_f32_e32 v51, v51
	v_mul_f32_e32 v50, v56, v50
	v_mul_f32_e32 v50, v50, v52
	v_mul_f32_e32 v52, 0xbfb8aa3b, v46
	v_exp_f32_e32 v52, v52
	v_mul_f32_e32 v51, v57, v51
	v_mul_f32_e32 v51, v51, v53
	v_cvt_pk_bf16_f32 v61, v50, v51
	v_add_f32_e32 v52, 1.0, v52
	v_rcp_f32_e32 v52, v52
	global_store_dwordx4 v[66:67], v[58:61], off sc1
	v_add_u32_e32 v50, 0x90, v152
	v_mad_i64_i32 v[50:51], s[14:15], v50, s52, v[144:145]
	v_mul_f32_e32 v46, v46, v52
	v_mul_f32_e32 v42, v46, v42
	v_mul_f32_e32 v46, 0xbfb8aa3b, v47
	v_exp_f32_e32 v46, v46
	v_lshl_add_u64 v[50:51], v[50:51], 0, v[146:147]
	v_add_f32_e32 v46, 1.0, v46
	v_rcp_f32_e32 v46, v46
	s_nop 0
	v_mul_f32_e32 v46, v47, v46
	v_mul_f32_e32 v43, v46, v43
	v_cvt_pk_bf16_f32 v42, v42, v43
	v_mul_f32_e32 v43, 0xbfb8aa3b, v48
	v_exp_f32_e32 v43, v43
	s_nop 0
	v_add_f32_e32 v43, 1.0, v43
	v_rcp_f32_e32 v43, v43
	s_nop 0
	v_mul_f32_e32 v43, v48, v43
	v_mul_f32_e32 v43, v43, v44
	v_mul_f32_e32 v44, 0xbfb8aa3b, v49
	v_exp_f32_e32 v44, v44
	s_nop 0
	v_add_f32_e32 v44, 1.0, v44
	v_rcp_f32_e32 v44, v44
	s_nop 0
	v_mul_f32_e32 v44, v49, v44
	v_mul_f32_e32 v44, v44, v45
	v_cvt_pk_bf16_f32 v43, v43, v44
	v_mul_f32_e32 v44, 0xbfb8aa3b, v38
	v_exp_f32_e32 v44, v44
	s_nop 0
	v_add_f32_e32 v44, 1.0, v44
	v_rcp_f32_e32 v44, v44
	s_nop 0
	v_mul_f32_e32 v38, v38, v44
	v_mul_f32_e32 v34, v38, v34
	v_mul_f32_e32 v38, 0xbfb8aa3b, v39
	v_exp_f32_e32 v38, v38
	s_nop 0
	v_add_f32_e32 v38, 1.0, v38
	v_rcp_f32_e32 v38, v38
	s_nop 0
	v_mul_f32_e32 v38, v39, v38
	v_mul_f32_e32 v35, v38, v35
	v_cvt_pk_bf16_f32 v44, v34, v35
	v_mul_f32_e32 v34, 0xbfb8aa3b, v40
	v_exp_f32_e32 v34, v34
	v_mul_f32_e32 v35, 0xbfb8aa3b, v41
	v_exp_f32_e32 v35, v35
	v_add_f32_e32 v34, 1.0, v34
	v_rcp_f32_e32 v34, v34
	v_add_f32_e32 v35, 1.0, v35
	v_rcp_f32_e32 v35, v35
	v_mul_f32_e32 v34, v40, v34
	v_mul_f32_e32 v34, v34, v36
	v_mul_f32_e32 v36, 0xbfb8aa3b, v30
	v_exp_f32_e32 v36, v36
	v_mul_f32_e32 v35, v41, v35
	v_mul_f32_e32 v35, v35, v37
	v_cvt_pk_bf16_f32 v45, v34, v35
	v_add_f32_e32 v36, 1.0, v36
	v_rcp_f32_e32 v36, v36
	global_store_dwordx4 v[50:51], v[42:45], off sc1
	v_add_u32_e32 v34, 0xa0, v152
	v_mad_i64_i32 v[34:35], s[14:15], v34, s52, v[144:145]
	v_mul_f32_e32 v30, v30, v36
	v_mul_f32_e32 v26, v30, v26
	v_mul_f32_e32 v30, 0xbfb8aa3b, v31
	v_exp_f32_e32 v30, v30
	v_lshl_add_u64 v[34:35], v[34:35], 0, v[146:147]
	v_add_f32_e32 v30, 1.0, v30
	v_rcp_f32_e32 v30, v30
	s_nop 0
	v_mul_f32_e32 v30, v31, v30
	v_mul_f32_e32 v27, v30, v27
	v_cvt_pk_bf16_f32 v26, v26, v27
	v_mul_f32_e32 v27, 0xbfb8aa3b, v32
	v_exp_f32_e32 v27, v27
	s_nop 0
	v_add_f32_e32 v27, 1.0, v27
	v_rcp_f32_e32 v27, v27
	s_nop 0
	v_mul_f32_e32 v27, v32, v27
	v_mul_f32_e32 v27, v27, v28
	v_mul_f32_e32 v28, 0xbfb8aa3b, v33
	v_exp_f32_e32 v28, v28
	s_nop 0
	v_add_f32_e32 v28, 1.0, v28
	v_rcp_f32_e32 v28, v28
	s_nop 0
	v_mul_f32_e32 v28, v33, v28
	v_mul_f32_e32 v28, v28, v29
	v_cvt_pk_bf16_f32 v27, v27, v28
	v_mul_f32_e32 v28, 0xbfb8aa3b, v22
	v_exp_f32_e32 v28, v28
	s_nop 0
	v_add_f32_e32 v28, 1.0, v28
	v_rcp_f32_e32 v28, v28
	s_nop 0
	v_mul_f32_e32 v22, v22, v28
	v_mul_f32_e32 v18, v22, v18
	v_mul_f32_e32 v22, 0xbfb8aa3b, v23
	v_exp_f32_e32 v22, v22
	s_nop 0
	v_add_f32_e32 v22, 1.0, v22
	v_rcp_f32_e32 v22, v22
	s_nop 0
	v_mul_f32_e32 v22, v23, v22
	v_mul_f32_e32 v19, v22, v19
	v_cvt_pk_bf16_f32 v28, v18, v19
	v_mul_f32_e32 v18, 0xbfb8aa3b, v24
	v_exp_f32_e32 v18, v18
	v_mul_f32_e32 v19, 0xbfb8aa3b, v25
	v_exp_f32_e32 v19, v19
	v_add_f32_e32 v18, 1.0, v18
	v_rcp_f32_e32 v18, v18
	v_add_f32_e32 v19, 1.0, v19
	v_rcp_f32_e32 v19, v19
	v_mul_f32_e32 v18, v24, v18
	v_mul_f32_e32 v18, v18, v20
	v_mul_f32_e32 v20, 0xbfb8aa3b, v14
	v_exp_f32_e32 v20, v20
	v_mul_f32_e32 v19, v25, v19
	v_mul_f32_e32 v19, v19, v21
	v_cvt_pk_bf16_f32 v29, v18, v19
	v_add_f32_e32 v20, 1.0, v20
	v_rcp_f32_e32 v20, v20
	global_store_dwordx4 v[34:35], v[26:29], off sc1
	v_add_u32_e32 v18, 0xb0, v152
	v_mad_i64_i32 v[18:19], s[14:15], v18, s52, v[144:145]
	v_mul_f32_e32 v14, v14, v20
	v_mul_f32_e32 v10, v14, v10
	v_mul_f32_e32 v14, 0xbfb8aa3b, v15
	v_exp_f32_e32 v14, v14
	v_lshl_add_u64 v[18:19], v[18:19], 0, v[146:147]
	s_mov_b64 s[14:15], s[10:11]
	v_add_f32_e32 v14, 1.0, v14
	v_rcp_f32_e32 v14, v14
	s_nop 0
	v_mul_f32_e32 v14, v15, v14
	v_mul_f32_e32 v11, v14, v11
	v_cvt_pk_bf16_f32 v10, v10, v11
	v_mul_f32_e32 v11, 0xbfb8aa3b, v16
	v_exp_f32_e32 v11, v11
	s_nop 0
	v_add_f32_e32 v11, 1.0, v11
	v_rcp_f32_e32 v11, v11
	s_nop 0
	v_mul_f32_e32 v11, v16, v11
	v_mul_f32_e32 v11, v11, v12
	v_mul_f32_e32 v12, 0xbfb8aa3b, v17
	v_exp_f32_e32 v12, v12
	s_nop 0
	v_add_f32_e32 v12, 1.0, v12
	v_rcp_f32_e32 v12, v12
	s_nop 0
	v_mul_f32_e32 v12, v17, v12
	v_mul_f32_e32 v12, v12, v13
	v_cvt_pk_bf16_f32 v11, v11, v12
	v_mul_f32_e32 v12, 0xbfb8aa3b, v6
	v_exp_f32_e32 v12, v12
	s_nop 0
	v_add_f32_e32 v12, 1.0, v12
	v_rcp_f32_e32 v12, v12
	s_nop 0
	v_mul_f32_e32 v6, v6, v12
	v_mul_f32_e32 v2, v6, v2
	v_mul_f32_e32 v6, 0xbfb8aa3b, v7
	v_exp_f32_e32 v6, v6
	s_nop 0
	v_add_f32_e32 v6, 1.0, v6
	v_rcp_f32_e32 v6, v6
	s_nop 0
	v_mul_f32_e32 v6, v7, v6
	v_mul_f32_e32 v3, v6, v3
	v_cvt_pk_bf16_f32 v12, v2, v3
	v_mul_f32_e32 v2, 0xbfb8aa3b, v8
	v_mul_f32_e32 v3, 0xbfb8aa3b, v9
	v_exp_f32_e32 v2, v2
	v_exp_f32_e32 v3, v3
	v_add_f32_e32 v2, 1.0, v2
	v_add_f32_e32 v3, 1.0, v3
	v_rcp_f32_e32 v2, v2
	v_rcp_f32_e32 v3, v3
	v_mul_f32_e32 v2, v8, v2
	v_mul_f32_e32 v3, v9, v3
	v_mul_f32_e32 v2, v2, v4
	v_mul_f32_e32 v3, v3, v5
	v_cvt_pk_bf16_f32 v13, v2, v3
	global_store_dwordx4 v[18:19], v[10:13], off sc1
	s_cbranch_vccz .LBB0_1126
	s_waitcnt vmcnt(0)
	s_cmpk_gt_u32 s2, 0xff
	s_cbranch_scc1 .LBB0_1133
	s_barrier
